# GEMM main loops: the compiler's lgkmcnt(0) that directly repeats the source's own wait before each MMA block dropped (36 instructions incl. peeled copies)
# speedup vs baseline: 1.0086x; 1.0086x over previous
.LBB0_490:
	v_mov_b64_e32 v[2:3], s[26:27]
	s_ashr_i32 s41, s40, 31
	v_cmp_lt_i64_e32 vcc, s[16:17], v[2:3]
	s_lshl_b64 s[16:17], s[40:41], 19
	s_add_u32 s44, s46, s16
	s_addc_u32 s45, s47, s17
	s_and_b64 s[16:17], vcc, exec
	s_cselect_b32 s9, s45, s13
	s_cselect_b32 s11, s44, s12
	s_ashr_i32 s39, s38, 31
	s_lshl_b64 s[16:17], s[38:39], 19
	s_add_u32 s54, s71, s16
	s_addc_u32 s55, s73, s17
	s_and_b64 s[16:17], vcc, exec
	s_cselect_b32 s39, s55, s15
	s_cselect_b32 s41, s54, s14
	s_add_u32 s12, s12, 0x40080
	s_addc_u32 s13, s13, 0
	s_add_u32 s62, s14, 0x100
	s_addc_u32 s63, s15, 0
	s_mov_b32 s64, -2
	s_add_u32 s14, s12, 0xfffc0080
	s_addc_u32 s15, s13, -1
	s_add_i32 s65, 0, 0x10000
	v_add_u32_e32 v0, s65, v230
	ds_read_b128 v[2:5], v0
	ds_read_b128 v[6:9], v0 offset:1024
	ds_read_b128 v[10:13], v0 offset:2048
	ds_read_b128 v[14:17], v0 offset:3072
	s_cmp_eq_u32 s64, 12
	s_cselect_b32 s17, s9, s15
	s_cselect_b32 s16, s11, s14
	s_cselect_b32 s15, s39, s63
	s_cselect_b32 s14, s41, s62
	v_lshl_add_u64 v[50:51], s[12:13], 0, v[214:215]
	s_add_i32 m0, s23, 0xc000
	ds_read_b128 v[18:21], v232
	ds_read_b128 v[22:25], v232 offset:1024
	ds_read_b128 v[26:29], v232 offset:2048
	ds_read_b128 v[30:33], v232 offset:3072
	ds_read_b128 v[34:37], v232 offset:4096
	ds_read_b128 v[38:41], v232 offset:5120
	ds_read_b128 v[42:45], v232 offset:6144
	ds_read_b128 v[46:49], v232 offset:7168
	global_load_lds_dwordx4 v[50:51], off
	v_lshl_add_u64 v[50:51], s[12:13], 0, v[216:217]
	s_add_i32 m0, s23, 0xe000
	s_nop 0
	global_load_lds_dwordx4 v[50:51], off
	s_waitcnt lgkmcnt(8)
	s_barrier
	s_waitcnt lgkmcnt(0)
	v_mfma_f32_16x16x32_bf16 v[158:161], v[2:5], v[34:37], 0
	v_mfma_f32_16x16x32_bf16 v[154:157], v[10:13], v[34:37], 0
	v_mfma_f32_16x16x32_bf16 v[138:141], v[2:5], v[42:45], 0
	v_mfma_f32_16x16x32_bf16 v[134:137], v[10:13], v[42:45], 0
	v_mfma_f32_16x16x32_bf16 v[50:53], v[2:5], v[18:21], 0
	v_mfma_f32_16x16x32_bf16 v[54:57], v[10:13], v[18:21], 0
	v_mfma_f32_16x16x32_bf16 v[58:61], v[2:5], v[26:29], 0
	v_mfma_f32_16x16x32_bf16 v[150:153], v[10:13], v[26:29], 0
	v_mfma_f32_16x16x32_bf16 v[158:161], v[6:9], v[38:41], v[158:161]
	v_mfma_f32_16x16x32_bf16 v[154:157], v[14:17], v[38:41], v[154:157]
	v_mfma_f32_16x16x32_bf16 v[138:141], v[6:9], v[46:49], v[138:141]
	v_mfma_f32_16x16x32_bf16 v[134:137], v[14:17], v[46:49], v[134:137]
	v_mfma_f32_16x16x32_bf16 v[50:53], v[6:9], v[22:25], v[50:53]
	v_mfma_f32_16x16x32_bf16 v[54:57], v[14:17], v[22:25], v[54:57]
	v_mfma_f32_16x16x32_bf16 v[58:61], v[6:9], v[30:33], v[58:61]
	v_mfma_f32_16x16x32_bf16 v[150:153], v[14:17], v[30:33], v[150:153]
	s_barrier
	s_add_i32 s86, 0, 0x14000
	s_add_i32 s65, s65, s22
	v_add_u32_e32 v0, s86, v230
	v_lshl_add_u64 v[222:223], s[14:15], 0, v[208:209]
	s_mov_b32 m0, s65
	ds_read_b128 v[162:165], v0
	ds_read_b128 v[174:177], v0 offset:1024
	ds_read_b128 v[178:181], v0 offset:2048
	ds_read_b128 v[182:185], v0 offset:3072
	global_load_lds_dwordx4 v[222:223], off
	v_lshl_add_u64 v[226:227], s[14:15], 0, v[212:213]
	s_add_i32 m0, s65, 0x2000
	s_nop 0
	global_load_lds_dwordx4 v[226:227], off
	s_barrier
	s_waitcnt lgkmcnt(0)
	v_mfma_f32_16x16x32_bf16 v[186:189], v[162:165], v[18:21], 0
	v_mfma_f32_16x16x32_bf16 v[18:21], v[178:181], v[18:21], 0
	v_mfma_f32_16x16x32_bf16 v[186:189], v[174:177], v[22:25], v[186:189]
	v_mfma_f32_16x16x32_bf16 v[18:21], v[182:185], v[22:25], v[18:21]
	v_mfma_f32_16x16x32_bf16 v[22:25], v[162:165], v[26:29], 0
	v_mfma_f32_16x16x32_bf16 v[26:29], v[178:181], v[26:29], 0
	v_mfma_f32_16x16x32_bf16 v[22:25], v[174:177], v[30:33], v[22:25]
	v_mfma_f32_16x16x32_bf16 v[26:29], v[182:185], v[30:33], v[26:29]
	v_mfma_f32_16x16x32_bf16 v[30:33], v[162:165], v[34:37], 0
	v_mfma_f32_16x16x32_bf16 v[34:37], v[178:181], v[34:37], 0
	v_mfma_f32_16x16x32_bf16 v[30:33], v[174:177], v[38:41], v[30:33]
	v_mfma_f32_16x16x32_bf16 v[34:37], v[182:185], v[38:41], v[34:37]
	v_mfma_f32_16x16x32_bf16 v[38:41], v[162:165], v[42:45], 0
	v_mfma_f32_16x16x32_bf16 v[42:45], v[178:181], v[42:45], 0
	v_mfma_f32_16x16x32_bf16 v[38:41], v[174:177], v[46:49], v[38:41]
	v_mfma_f32_16x16x32_bf16 v[42:45], v[182:185], v[46:49], v[42:45]
	s_mov_b32 m0, s23
	v_lshl_add_u64 v[238:239], s[16:17], 0, v[206:207]
	s_barrier
	ds_read_b128 v[46:49], v232 offset:16384
	ds_read_b128 v[126:129], v232 offset:17408
	ds_read_b128 v[130:133], v232 offset:18432
	ds_read_b128 v[142:145], v232 offset:19456
	ds_read_b128 v[146:149], v232 offset:20480
	ds_read_b128 v[166:169], v232 offset:21504
	ds_read_b128 v[170:173], v232 offset:22528
	ds_read_b128 v[190:193], v232 offset:23552
	global_load_lds_dwordx4 v[238:239], off
	v_lshl_add_u64 v[240:241], s[16:17], 0, v[210:211]
	s_mov_b32 m0, s72
	s_nop 0
	global_load_lds_dwordx4 v[240:241], off
	s_barrier
	s_waitcnt lgkmcnt(0)
	v_mfma_f32_16x16x32_bf16 v[122:125], v[2:5], v[46:49], 0
	v_mfma_f32_16x16x32_bf16 v[118:121], v[10:13], v[46:49], 0
	v_mfma_f32_16x16x32_bf16 v[106:109], v[2:5], v[130:133], 0
	v_mfma_f32_16x16x32_bf16 v[102:105], v[10:13], v[130:133], 0
	v_mfma_f32_16x16x32_bf16 v[90:93], v[2:5], v[146:149], 0
	v_mfma_f32_16x16x32_bf16 v[86:89], v[10:13], v[146:149], 0
	v_mfma_f32_16x16x32_bf16 v[2:5], v[2:5], v[170:173], 0
	v_mfma_f32_16x16x32_bf16 v[122:125], v[6:9], v[126:129], v[122:125]
	v_mfma_f32_16x16x32_bf16 v[118:121], v[14:17], v[126:129], v[118:121]
	v_mfma_f32_16x16x32_bf16 v[106:109], v[6:9], v[142:145], v[106:109]
	v_mfma_f32_16x16x32_bf16 v[102:105], v[14:17], v[142:145], v[102:105]
	v_mfma_f32_16x16x32_bf16 v[90:93], v[6:9], v[166:169], v[90:93]
	v_mfma_f32_16x16x32_bf16 v[86:89], v[14:17], v[166:169], v[86:89]
	v_mfma_f32_16x16x32_bf16 v[2:5], v[6:9], v[190:193], v[2:5]
	v_mfma_f32_16x16x32_bf16 v[6:9], v[10:13], v[170:173], 0
	v_mfma_f32_16x16x32_bf16 v[6:9], v[14:17], v[190:193], v[6:9]
	s_barrier
	s_add_u32 s66, s14, 0x40000
	s_addc_u32 s67, s15, 0
	s_add_i32 s65, s86, s22
	v_lshl_add_u64 v[10:11], s[66:67], 0, v[208:209]
	s_mov_b32 m0, s65
	s_nop 0
	global_load_lds_dwordx4 v[10:11], off
	v_lshl_add_u64 v[10:11], s[66:67], 0, v[212:213]
	s_add_i32 m0, s65, 0x2000
	s_nop 0
	global_load_lds_dwordx4 v[10:11], off
	s_waitcnt vmcnt(6)
	s_barrier
	v_mfma_f32_16x16x32_bf16 v[70:73], v[178:181], v[130:133], 0
	v_mfma_f32_16x16x32_bf16 v[94:97], v[182:185], v[142:145], v[70:73]
	v_mfma_f32_16x16x32_bf16 v[70:73], v[162:165], v[146:149], 0
	v_mfma_f32_16x16x32_bf16 v[82:85], v[174:177], v[166:169], v[70:73]
	v_mfma_f32_16x16x32_bf16 v[70:73], v[178:181], v[146:149], 0
	v_mfma_f32_16x16x32_bf16 v[66:69], v[162:165], v[170:173], 0
	v_mfma_f32_16x16x32_bf16 v[62:65], v[178:181], v[170:173], 0
	v_mfma_f32_16x16x32_bf16 v[10:13], v[162:165], v[46:49], 0
	v_mfma_f32_16x16x32_bf16 v[14:17], v[178:181], v[46:49], 0
	v_mfma_f32_16x16x32_bf16 v[46:49], v[162:165], v[130:133], 0
	v_mfma_f32_16x16x32_bf16 v[78:81], v[182:185], v[166:169], v[70:73]
	v_mfma_f32_16x16x32_bf16 v[66:69], v[174:177], v[190:193], v[66:69]
	v_mfma_f32_16x16x32_bf16 v[62:65], v[182:185], v[190:193], v[62:65]
	v_mfma_f32_16x16x32_bf16 v[10:13], v[174:177], v[126:129], v[10:13]
	v_mfma_f32_16x16x32_bf16 v[14:17], v[182:185], v[126:129], v[14:17]
	v_mfma_f32_16x16x32_bf16 v[46:49], v[174:177], v[142:145], v[46:49]
	s_add_i32 s65, 0, 0x18000
	v_add_u32_e32 v0, s65, v230
	s_barrier
	ds_read_b128 v[70:73], v0
	ds_read_b128 v[74:77], v0 offset:1024
	ds_read_b128 v[98:101], v0 offset:2048
	ds_read_b128 v[110:113], v0 offset:3072
	s_add_u32 s16, s16, 0x40000
	s_addc_u32 s17, s17, 0
	s_mov_b32 m0, s83
	v_lshl_add_u64 v[146:147], s[16:17], 0, v[206:207]
	ds_read_b128 v[114:117], v232 offset:32768
	ds_read_b128 v[126:129], v232 offset:33792
	ds_read_b128 v[130:133], v232 offset:34816
	ds_read_b128 v[142:145], v232 offset:35840
	ds_read_b128 v[162:165], v232 offset:36864
	ds_read_b128 v[174:177], v232 offset:37888
	ds_read_b128 v[218:221], v232 offset:38912
	ds_read_b128 v[234:237], v232 offset:39936
	global_load_lds_dwordx4 v[146:147], off
	v_lshl_add_u64 v[146:147], s[16:17], 0, v[210:211]
	s_mov_b32 m0, s84
	s_nop 0
	global_load_lds_dwordx4 v[146:147], off
	s_waitcnt lgkmcnt(8)
	s_barrier
	s_waitcnt lgkmcnt(0)
	v_mfma_f32_16x16x32_bf16 v[50:53], v[70:73], v[114:117], v[50:53]
	v_mfma_f32_16x16x32_bf16 v[202:205], v[74:77], v[126:129], v[50:53]
	v_mfma_f32_16x16x32_bf16 v[50:53], v[98:101], v[114:117], v[54:57]
	v_mfma_f32_16x16x32_bf16 v[198:201], v[110:113], v[126:129], v[50:53]
	v_mfma_f32_16x16x32_bf16 v[50:53], v[70:73], v[130:133], v[58:61]
	v_mfma_f32_16x16x32_bf16 v[182:185], v[74:77], v[142:145], v[50:53]
	v_mfma_f32_16x16x32_bf16 v[50:53], v[98:101], v[130:133], v[150:153]
	v_mfma_f32_16x16x32_bf16 v[178:181], v[110:113], v[142:145], v[50:53]
	v_mfma_f32_16x16x32_bf16 v[50:53], v[70:73], v[162:165], v[158:161]
	v_mfma_f32_16x16x32_bf16 v[158:161], v[74:77], v[174:177], v[50:53]
	v_mfma_f32_16x16x32_bf16 v[50:53], v[98:101], v[162:165], v[154:157]
	v_mfma_f32_16x16x32_bf16 v[154:157], v[110:113], v[174:177], v[50:53]
	v_mfma_f32_16x16x32_bf16 v[50:53], v[70:73], v[218:221], v[138:141]
	v_mfma_f32_16x16x32_bf16 v[138:141], v[74:77], v[234:237], v[50:53]
	v_mfma_f32_16x16x32_bf16 v[50:53], v[98:101], v[218:221], v[134:137]
	v_mfma_f32_16x16x32_bf16 v[134:137], v[110:113], v[234:237], v[50:53]
	s_barrier
	s_add_i32 s16, 0, 0x1c000
	s_add_i32 s17, s65, s22
	v_add_u32_e32 v0, s16, v230
	v_lshl_add_u64 v[146:147], v[222:223], 0, s[20:21]
	s_mov_b32 m0, s17
	ds_read_b128 v[50:53], v0
	ds_read_b128 v[54:57], v0 offset:1024
	ds_read_b128 v[58:61], v0 offset:2048
	ds_read_b128 v[150:153], v0 offset:3072
	global_load_lds_dwordx4 v[146:147], off
	v_lshl_add_u64 v[146:147], v[226:227], 0, s[20:21]
	s_add_i32 m0, s17, 0x2000
	s_nop 0
	global_load_lds_dwordx4 v[146:147], off
	s_barrier
	s_waitcnt lgkmcnt(0)
	v_mfma_f32_16x16x32_bf16 v[18:21], v[58:61], v[114:117], v[18:21]
	v_mfma_f32_16x16x32_bf16 v[190:193], v[150:153], v[126:129], v[18:21]
	v_mfma_f32_16x16x32_bf16 v[18:21], v[50:53], v[130:133], v[22:25]
	v_mfma_f32_16x16x32_bf16 v[170:173], v[54:57], v[142:145], v[18:21]
	v_mfma_f32_16x16x32_bf16 v[18:21], v[58:61], v[130:133], v[26:29]
	v_mfma_f32_16x16x32_bf16 v[146:149], v[50:53], v[114:117], v[186:189]
	v_mfma_f32_16x16x32_bf16 v[166:169], v[150:153], v[142:145], v[18:21]
	v_mfma_f32_16x16x32_bf16 v[18:21], v[50:53], v[162:165], v[30:33]
	v_mfma_f32_16x16x32_bf16 v[194:197], v[54:57], v[126:129], v[146:149]
	v_mfma_f32_16x16x32_bf16 v[146:149], v[54:57], v[174:177], v[18:21]
	v_mfma_f32_16x16x32_bf16 v[18:21], v[58:61], v[162:165], v[34:37]
	v_mfma_f32_16x16x32_bf16 v[142:145], v[150:153], v[174:177], v[18:21]
	v_mfma_f32_16x16x32_bf16 v[18:21], v[50:53], v[218:221], v[38:41]
	v_mfma_f32_16x16x32_bf16 v[130:133], v[54:57], v[234:237], v[18:21]
	v_mfma_f32_16x16x32_bf16 v[18:21], v[58:61], v[218:221], v[42:45]
	v_mfma_f32_16x16x32_bf16 v[126:129], v[150:153], v[234:237], v[18:21]
	s_mov_b32 m0, s91
	v_lshl_add_u64 v[114:115], v[238:239], 0, s[20:21]
	s_barrier
	s_nop 2
	ds_read_b128 v[18:21], v232 offset:49152
	ds_read_b128 v[22:25], v232 offset:50176
	ds_read_b128 v[26:29], v232 offset:51200
	ds_read_b128 v[30:33], v232 offset:52224
	ds_read_b128 v[34:37], v232 offset:53248
	ds_read_b128 v[38:41], v232 offset:54272
	ds_read_b128 v[42:45], v232 offset:55296
	ds_read_b128 v[162:165], v232 offset:56320
	global_load_lds_dwordx4 v[114:115], off
	v_lshl_add_u64 v[114:115], v[240:241], 0, s[20:21]
	s_mov_b32 m0, s59
	s_nop 0
	global_load_lds_dwordx4 v[114:115], off
	s_barrier
	s_waitcnt lgkmcnt(0)
	v_mfma_f32_16x16x32_bf16 v[114:117], v[70:73], v[18:21], v[122:125]
	v_mfma_f32_16x16x32_bf16 v[106:109], v[70:73], v[26:29], v[106:109]
	v_mfma_f32_16x16x32_bf16 v[90:93], v[70:73], v[34:37], v[90:93]
	v_mfma_f32_16x16x32_bf16 v[2:5], v[70:73], v[42:45], v[2:5]
	v_mfma_f32_16x16x32_bf16 v[122:125], v[74:77], v[22:25], v[114:117]
	v_mfma_f32_16x16x32_bf16 v[114:117], v[98:101], v[18:21], v[118:121]
	v_mfma_f32_16x16x32_bf16 v[106:109], v[74:77], v[30:33], v[106:109]
	v_mfma_f32_16x16x32_bf16 v[102:105], v[98:101], v[26:29], v[102:105]
	v_mfma_f32_16x16x32_bf16 v[90:93], v[74:77], v[38:41], v[90:93]
	v_mfma_f32_16x16x32_bf16 v[86:89], v[98:101], v[34:37], v[86:89]
	v_mfma_f32_16x16x32_bf16 v[74:77], v[74:77], v[162:165], v[2:5]
	v_mfma_f32_16x16x32_bf16 v[2:5], v[98:101], v[42:45], v[6:9]
	v_mfma_f32_16x16x32_bf16 v[118:121], v[110:113], v[22:25], v[114:117]
	v_mfma_f32_16x16x32_bf16 v[102:105], v[110:113], v[30:33], v[102:105]
	v_mfma_f32_16x16x32_bf16 v[86:89], v[110:113], v[38:41], v[86:89]
	v_mfma_f32_16x16x32_bf16 v[70:73], v[110:113], v[162:165], v[2:5]
	s_barrier
	s_add_u32 s14, s14, 0x40080
	s_addc_u32 s15, s15, 0
	s_add_i32 s16, s16, s22
	v_lshl_add_u64 v[2:3], s[14:15], 0, v[208:209]
	s_mov_b32 m0, s16
	s_nop 0
	global_load_lds_dwordx4 v[2:3], off
	v_lshl_add_u64 v[2:3], s[14:15], 0, v[212:213]
	s_add_i32 m0, s16, 0x2000
	s_nop 0
	global_load_lds_dwordx4 v[2:3], off
	s_waitcnt vmcnt(6)
	s_barrier
	v_mfma_f32_16x16x32_bf16 v[2:5], v[50:53], v[18:21], v[10:13]
	v_mfma_f32_16x16x32_bf16 v[114:117], v[54:57], v[22:25], v[2:5]
	v_mfma_f32_16x16x32_bf16 v[2:5], v[58:61], v[18:21], v[14:17]
	v_mfma_f32_16x16x32_bf16 v[110:113], v[150:153], v[22:25], v[2:5]
	v_mfma_f32_16x16x32_bf16 v[2:5], v[50:53], v[26:29], v[46:49]
	v_mfma_f32_16x16x32_bf16 v[98:101], v[54:57], v[30:33], v[2:5]
	v_mfma_f32_16x16x32_bf16 v[2:5], v[58:61], v[26:29], v[94:97]
	v_mfma_f32_16x16x32_bf16 v[94:97], v[150:153], v[30:33], v[2:5]
	v_mfma_f32_16x16x32_bf16 v[2:5], v[50:53], v[34:37], v[82:85]
	v_mfma_f32_16x16x32_bf16 v[82:85], v[54:57], v[38:41], v[2:5]
	v_mfma_f32_16x16x32_bf16 v[2:5], v[58:61], v[34:37], v[78:81]
	v_mfma_f32_16x16x32_bf16 v[78:81], v[150:153], v[38:41], v[2:5]
	v_mfma_f32_16x16x32_bf16 v[2:5], v[50:53], v[42:45], v[66:69]
	v_mfma_f32_16x16x32_bf16 v[66:69], v[54:57], v[162:165], v[2:5]
	v_mfma_f32_16x16x32_bf16 v[2:5], v[58:61], v[42:45], v[62:65]
	v_mfma_f32_16x16x32_bf16 v[62:65], v[150:153], v[162:165], v[2:5]
	s_add_i32 s64, s64, 2
	s_add_u32 s12, s12, 0x100
	s_addc_u32 s13, s13, 0
	s_add_u32 s62, s62, 0x100
	s_addc_u32 s63, s63, 0
	s_cmp_gt_u32 s64, 13
	s_barrier
	s_cbranch_scc0 .LBB0_491
	s_branch .Lpeel_exit_g1
.LBB0_491:
	s_add_u32 s14, s12, 0xfffc0080
	s_addc_u32 s15, s13, -1
	s_add_i32 s65, 0, 0x10000
	v_add_u32_e32 v0, s65, v230
	ds_read_b128 v[2:5], v0
	ds_read_b128 v[6:9], v0 offset:1024
	ds_read_b128 v[10:13], v0 offset:2048
	ds_read_b128 v[14:17], v0 offset:3072
	s_cmp_eq_u32 s64, 12
	s_cselect_b32 s17, s9, s15
	s_cselect_b32 s16, s11, s14
	s_cselect_b32 s15, s39, s63
	s_cselect_b32 s14, s41, s62
	v_lshl_add_u64 v[50:51], s[12:13], 0, v[214:215]
	s_add_i32 m0, s23, 0xc000
	ds_read_b128 v[18:21], v232
	ds_read_b128 v[22:25], v232 offset:1024
	ds_read_b128 v[26:29], v232 offset:2048
	ds_read_b128 v[30:33], v232 offset:3072
	ds_read_b128 v[34:37], v232 offset:4096
	ds_read_b128 v[38:41], v232 offset:5120
	ds_read_b128 v[42:45], v232 offset:6144
	ds_read_b128 v[46:49], v232 offset:7168
	global_load_lds_dwordx4 v[50:51], off
	v_lshl_add_u64 v[50:51], s[12:13], 0, v[216:217]
	s_add_i32 m0, s23, 0xe000
	s_nop 0
	global_load_lds_dwordx4 v[50:51], off
	s_waitcnt lgkmcnt(8)
	s_barrier
	s_waitcnt lgkmcnt(0)
	v_mfma_f32_16x16x32_bf16 v[158:161], v[2:5], v[34:37], v[158:161]
	v_mfma_f32_16x16x32_bf16 v[154:157], v[10:13], v[34:37], v[154:157]
	v_mfma_f32_16x16x32_bf16 v[138:141], v[2:5], v[42:45], v[138:141]
	v_mfma_f32_16x16x32_bf16 v[134:137], v[10:13], v[42:45], v[134:137]
	v_mfma_f32_16x16x32_bf16 v[50:53], v[2:5], v[18:21], v[202:205]
	v_mfma_f32_16x16x32_bf16 v[54:57], v[10:13], v[18:21], v[198:201]
	v_mfma_f32_16x16x32_bf16 v[58:61], v[2:5], v[26:29], v[182:185]
	v_mfma_f32_16x16x32_bf16 v[150:153], v[10:13], v[26:29], v[178:181]
	v_mfma_f32_16x16x32_bf16 v[158:161], v[6:9], v[38:41], v[158:161]
	v_mfma_f32_16x16x32_bf16 v[154:157], v[14:17], v[38:41], v[154:157]
	v_mfma_f32_16x16x32_bf16 v[138:141], v[6:9], v[46:49], v[138:141]
	v_mfma_f32_16x16x32_bf16 v[134:137], v[14:17], v[46:49], v[134:137]
	v_mfma_f32_16x16x32_bf16 v[50:53], v[6:9], v[22:25], v[50:53]
	v_mfma_f32_16x16x32_bf16 v[54:57], v[14:17], v[22:25], v[54:57]
	v_mfma_f32_16x16x32_bf16 v[58:61], v[6:9], v[30:33], v[58:61]
	v_mfma_f32_16x16x32_bf16 v[150:153], v[14:17], v[30:33], v[150:153]
	s_barrier
	s_add_i32 s86, 0, 0x14000
	s_add_i32 s65, s65, s22
	v_add_u32_e32 v0, s86, v230
	v_lshl_add_u64 v[222:223], s[14:15], 0, v[208:209]
	s_mov_b32 m0, s65
	ds_read_b128 v[162:165], v0
	ds_read_b128 v[174:177], v0 offset:1024
	ds_read_b128 v[178:181], v0 offset:2048
	ds_read_b128 v[182:185], v0 offset:3072
	global_load_lds_dwordx4 v[222:223], off
	v_lshl_add_u64 v[226:227], s[14:15], 0, v[212:213]
	s_add_i32 m0, s65, 0x2000
	s_nop 0
	global_load_lds_dwordx4 v[226:227], off
	s_barrier
	s_waitcnt lgkmcnt(0)
	v_mfma_f32_16x16x32_bf16 v[186:189], v[162:165], v[18:21], v[194:197]
	v_mfma_f32_16x16x32_bf16 v[18:21], v[178:181], v[18:21], v[190:193]
	v_mfma_f32_16x16x32_bf16 v[186:189], v[174:177], v[22:25], v[186:189]
	v_mfma_f32_16x16x32_bf16 v[18:21], v[182:185], v[22:25], v[18:21]
	v_mfma_f32_16x16x32_bf16 v[22:25], v[162:165], v[26:29], v[170:173]
	v_mfma_f32_16x16x32_bf16 v[26:29], v[178:181], v[26:29], v[166:169]
	v_mfma_f32_16x16x32_bf16 v[22:25], v[174:177], v[30:33], v[22:25]
	v_mfma_f32_16x16x32_bf16 v[26:29], v[182:185], v[30:33], v[26:29]
	v_mfma_f32_16x16x32_bf16 v[30:33], v[162:165], v[34:37], v[146:149]
	v_mfma_f32_16x16x32_bf16 v[34:37], v[178:181], v[34:37], v[142:145]
	v_mfma_f32_16x16x32_bf16 v[30:33], v[174:177], v[38:41], v[30:33]
	v_mfma_f32_16x16x32_bf16 v[34:37], v[182:185], v[38:41], v[34:37]
	v_mfma_f32_16x16x32_bf16 v[38:41], v[162:165], v[42:45], v[130:133]
	v_mfma_f32_16x16x32_bf16 v[42:45], v[178:181], v[42:45], v[126:129]
	v_mfma_f32_16x16x32_bf16 v[38:41], v[174:177], v[46:49], v[38:41]
	v_mfma_f32_16x16x32_bf16 v[42:45], v[182:185], v[46:49], v[42:45]
	s_mov_b32 m0, s23
	v_lshl_add_u64 v[238:239], s[16:17], 0, v[206:207]
	s_barrier
	ds_read_b128 v[46:49], v232 offset:16384
	ds_read_b128 v[126:129], v232 offset:17408
	ds_read_b128 v[130:133], v232 offset:18432
	ds_read_b128 v[142:145], v232 offset:19456
	ds_read_b128 v[146:149], v232 offset:20480
	ds_read_b128 v[166:169], v232 offset:21504
	ds_read_b128 v[170:173], v232 offset:22528
	ds_read_b128 v[190:193], v232 offset:23552
	global_load_lds_dwordx4 v[238:239], off
	v_lshl_add_u64 v[240:241], s[16:17], 0, v[210:211]
	s_mov_b32 m0, s72
	s_nop 0
	global_load_lds_dwordx4 v[240:241], off
	s_barrier
	s_waitcnt lgkmcnt(0)
	v_mfma_f32_16x16x32_bf16 v[122:125], v[2:5], v[46:49], v[122:125]
	v_mfma_f32_16x16x32_bf16 v[118:121], v[10:13], v[46:49], v[118:121]
	v_mfma_f32_16x16x32_bf16 v[106:109], v[2:5], v[130:133], v[106:109]
	v_mfma_f32_16x16x32_bf16 v[102:105], v[10:13], v[130:133], v[102:105]
	v_mfma_f32_16x16x32_bf16 v[90:93], v[2:5], v[146:149], v[90:93]
	v_mfma_f32_16x16x32_bf16 v[86:89], v[10:13], v[146:149], v[86:89]
	v_mfma_f32_16x16x32_bf16 v[2:5], v[2:5], v[170:173], v[74:77]
	v_mfma_f32_16x16x32_bf16 v[122:125], v[6:9], v[126:129], v[122:125]
	v_mfma_f32_16x16x32_bf16 v[118:121], v[14:17], v[126:129], v[118:121]
	v_mfma_f32_16x16x32_bf16 v[106:109], v[6:9], v[142:145], v[106:109]
	v_mfma_f32_16x16x32_bf16 v[102:105], v[14:17], v[142:145], v[102:105]
	v_mfma_f32_16x16x32_bf16 v[90:93], v[6:9], v[166:169], v[90:93]
	v_mfma_f32_16x16x32_bf16 v[86:89], v[14:17], v[166:169], v[86:89]
	v_mfma_f32_16x16x32_bf16 v[2:5], v[6:9], v[190:193], v[2:5]
	v_mfma_f32_16x16x32_bf16 v[6:9], v[10:13], v[170:173], v[70:73]
	v_mfma_f32_16x16x32_bf16 v[6:9], v[14:17], v[190:193], v[6:9]
	s_barrier
	s_add_u32 s66, s14, 0x40000
	s_addc_u32 s67, s15, 0
	s_add_i32 s65, s86, s22
	v_lshl_add_u64 v[10:11], s[66:67], 0, v[208:209]
	s_mov_b32 m0, s65
	s_nop 0
	global_load_lds_dwordx4 v[10:11], off
	v_lshl_add_u64 v[10:11], s[66:67], 0, v[212:213]
	s_add_i32 m0, s65, 0x2000
	s_nop 0
	global_load_lds_dwordx4 v[10:11], off
	s_waitcnt vmcnt(6)
	s_barrier
	v_mfma_f32_16x16x32_bf16 v[70:73], v[178:181], v[130:133], v[94:97]
	v_mfma_f32_16x16x32_bf16 v[94:97], v[182:185], v[142:145], v[70:73]
	v_mfma_f32_16x16x32_bf16 v[70:73], v[162:165], v[146:149], v[82:85]
	v_mfma_f32_16x16x32_bf16 v[82:85], v[174:177], v[166:169], v[70:73]
	v_mfma_f32_16x16x32_bf16 v[70:73], v[178:181], v[146:149], v[78:81]
	v_mfma_f32_16x16x32_bf16 v[66:69], v[162:165], v[170:173], v[66:69]
	v_mfma_f32_16x16x32_bf16 v[62:65], v[178:181], v[170:173], v[62:65]
	v_mfma_f32_16x16x32_bf16 v[10:13], v[162:165], v[46:49], v[114:117]
	v_mfma_f32_16x16x32_bf16 v[14:17], v[178:181], v[46:49], v[110:113]
	v_mfma_f32_16x16x32_bf16 v[46:49], v[162:165], v[130:133], v[98:101]
	v_mfma_f32_16x16x32_bf16 v[78:81], v[182:185], v[166:169], v[70:73]
	v_mfma_f32_16x16x32_bf16 v[66:69], v[174:177], v[190:193], v[66:69]
	v_mfma_f32_16x16x32_bf16 v[62:65], v[182:185], v[190:193], v[62:65]
	v_mfma_f32_16x16x32_bf16 v[10:13], v[174:177], v[126:129], v[10:13]
	v_mfma_f32_16x16x32_bf16 v[14:17], v[182:185], v[126:129], v[14:17]
	v_mfma_f32_16x16x32_bf16 v[46:49], v[174:177], v[142:145], v[46:49]
	s_add_i32 s65, 0, 0x18000
	v_add_u32_e32 v0, s65, v230
	s_barrier
	ds_read_b128 v[70:73], v0
	ds_read_b128 v[74:77], v0 offset:1024
	ds_read_b128 v[98:101], v0 offset:2048
	ds_read_b128 v[110:113], v0 offset:3072
	s_add_u32 s16, s16, 0x40000
	s_addc_u32 s17, s17, 0
	s_mov_b32 m0, s83
	v_lshl_add_u64 v[146:147], s[16:17], 0, v[206:207]
	ds_read_b128 v[114:117], v232 offset:32768
	ds_read_b128 v[126:129], v232 offset:33792
	ds_read_b128 v[130:133], v232 offset:34816
	ds_read_b128 v[142:145], v232 offset:35840
	ds_read_b128 v[162:165], v232 offset:36864
	ds_read_b128 v[174:177], v232 offset:37888
	ds_read_b128 v[218:221], v232 offset:38912
	ds_read_b128 v[234:237], v232 offset:39936
	global_load_lds_dwordx4 v[146:147], off
	v_lshl_add_u64 v[146:147], s[16:17], 0, v[210:211]
	s_mov_b32 m0, s84
	s_nop 0
	global_load_lds_dwordx4 v[146:147], off
	s_waitcnt lgkmcnt(8)
	s_barrier
	s_waitcnt lgkmcnt(0)
	v_mfma_f32_16x16x32_bf16 v[50:53], v[70:73], v[114:117], v[50:53]
	v_mfma_f32_16x16x32_bf16 v[202:205], v[74:77], v[126:129], v[50:53]
	v_mfma_f32_16x16x32_bf16 v[50:53], v[98:101], v[114:117], v[54:57]
	v_mfma_f32_16x16x32_bf16 v[198:201], v[110:113], v[126:129], v[50:53]
	v_mfma_f32_16x16x32_bf16 v[50:53], v[70:73], v[130:133], v[58:61]
	v_mfma_f32_16x16x32_bf16 v[182:185], v[74:77], v[142:145], v[50:53]
	v_mfma_f32_16x16x32_bf16 v[50:53], v[98:101], v[130:133], v[150:153]
	v_mfma_f32_16x16x32_bf16 v[178:181], v[110:113], v[142:145], v[50:53]
	v_mfma_f32_16x16x32_bf16 v[50:53], v[70:73], v[162:165], v[158:161]
	v_mfma_f32_16x16x32_bf16 v[158:161], v[74:77], v[174:177], v[50:53]
	v_mfma_f32_16x16x32_bf16 v[50:53], v[98:101], v[162:165], v[154:157]
	v_mfma_f32_16x16x32_bf16 v[154:157], v[110:113], v[174:177], v[50:53]
	v_mfma_f32_16x16x32_bf16 v[50:53], v[70:73], v[218:221], v[138:141]
	v_mfma_f32_16x16x32_bf16 v[138:141], v[74:77], v[234:237], v[50:53]
	v_mfma_f32_16x16x32_bf16 v[50:53], v[98:101], v[218:221], v[134:137]
	v_mfma_f32_16x16x32_bf16 v[134:137], v[110:113], v[234:237], v[50:53]
	s_barrier
	s_add_i32 s16, 0, 0x1c000
	s_add_i32 s17, s65, s22
	v_add_u32_e32 v0, s16, v230
	v_lshl_add_u64 v[146:147], v[222:223], 0, s[20:21]
	s_mov_b32 m0, s17
	ds_read_b128 v[50:53], v0
	ds_read_b128 v[54:57], v0 offset:1024
	ds_read_b128 v[58:61], v0 offset:2048
	ds_read_b128 v[150:153], v0 offset:3072
	global_load_lds_dwordx4 v[146:147], off
	v_lshl_add_u64 v[146:147], v[226:227], 0, s[20:21]
	s_add_i32 m0, s17, 0x2000
	s_nop 0
	global_load_lds_dwordx4 v[146:147], off
	s_barrier
	s_waitcnt lgkmcnt(0)
	v_mfma_f32_16x16x32_bf16 v[18:21], v[58:61], v[114:117], v[18:21]
	v_mfma_f32_16x16x32_bf16 v[190:193], v[150:153], v[126:129], v[18:21]
	v_mfma_f32_16x16x32_bf16 v[18:21], v[50:53], v[130:133], v[22:25]
	v_mfma_f32_16x16x32_bf16 v[170:173], v[54:57], v[142:145], v[18:21]
	v_mfma_f32_16x16x32_bf16 v[18:21], v[58:61], v[130:133], v[26:29]
	v_mfma_f32_16x16x32_bf16 v[146:149], v[50:53], v[114:117], v[186:189]
	v_mfma_f32_16x16x32_bf16 v[166:169], v[150:153], v[142:145], v[18:21]
	v_mfma_f32_16x16x32_bf16 v[18:21], v[50:53], v[162:165], v[30:33]
	v_mfma_f32_16x16x32_bf16 v[194:197], v[54:57], v[126:129], v[146:149]
	v_mfma_f32_16x16x32_bf16 v[146:149], v[54:57], v[174:177], v[18:21]
	v_mfma_f32_16x16x32_bf16 v[18:21], v[58:61], v[162:165], v[34:37]
	v_mfma_f32_16x16x32_bf16 v[142:145], v[150:153], v[174:177], v[18:21]
	v_mfma_f32_16x16x32_bf16 v[18:21], v[50:53], v[218:221], v[38:41]
	v_mfma_f32_16x16x32_bf16 v[130:133], v[54:57], v[234:237], v[18:21]
	v_mfma_f32_16x16x32_bf16 v[18:21], v[58:61], v[218:221], v[42:45]
	v_mfma_f32_16x16x32_bf16 v[126:129], v[150:153], v[234:237], v[18:21]
	s_mov_b32 m0, s91
	v_lshl_add_u64 v[114:115], v[238:239], 0, s[20:21]
	s_barrier
	s_nop 2
	ds_read_b128 v[18:21], v232 offset:49152
	ds_read_b128 v[22:25], v232 offset:50176
	ds_read_b128 v[26:29], v232 offset:51200
	ds_read_b128 v[30:33], v232 offset:52224
	ds_read_b128 v[34:37], v232 offset:53248
	ds_read_b128 v[38:41], v232 offset:54272
	ds_read_b128 v[42:45], v232 offset:55296
	ds_read_b128 v[162:165], v232 offset:56320
	global_load_lds_dwordx4 v[114:115], off
	v_lshl_add_u64 v[114:115], v[240:241], 0, s[20:21]
	s_mov_b32 m0, s59
	s_nop 0
	global_load_lds_dwordx4 v[114:115], off
	s_barrier
	s_waitcnt lgkmcnt(0)
	v_mfma_f32_16x16x32_bf16 v[114:117], v[70:73], v[18:21], v[122:125]
	v_mfma_f32_16x16x32_bf16 v[106:109], v[70:73], v[26:29], v[106:109]
	v_mfma_f32_16x16x32_bf16 v[90:93], v[70:73], v[34:37], v[90:93]
	v_mfma_f32_16x16x32_bf16 v[2:5], v[70:73], v[42:45], v[2:5]
	v_mfma_f32_16x16x32_bf16 v[122:125], v[74:77], v[22:25], v[114:117]
	v_mfma_f32_16x16x32_bf16 v[114:117], v[98:101], v[18:21], v[118:121]
	v_mfma_f32_16x16x32_bf16 v[106:109], v[74:77], v[30:33], v[106:109]
	v_mfma_f32_16x16x32_bf16 v[102:105], v[98:101], v[26:29], v[102:105]
	v_mfma_f32_16x16x32_bf16 v[90:93], v[74:77], v[38:41], v[90:93]
	v_mfma_f32_16x16x32_bf16 v[86:89], v[98:101], v[34:37], v[86:89]
	v_mfma_f32_16x16x32_bf16 v[74:77], v[74:77], v[162:165], v[2:5]
	v_mfma_f32_16x16x32_bf16 v[2:5], v[98:101], v[42:45], v[6:9]
	v_mfma_f32_16x16x32_bf16 v[118:121], v[110:113], v[22:25], v[114:117]
	v_mfma_f32_16x16x32_bf16 v[102:105], v[110:113], v[30:33], v[102:105]
	v_mfma_f32_16x16x32_bf16 v[86:89], v[110:113], v[38:41], v[86:89]
	v_mfma_f32_16x16x32_bf16 v[70:73], v[110:113], v[162:165], v[2:5]
	s_barrier
	s_add_u32 s14, s14, 0x40080
	s_addc_u32 s15, s15, 0
	s_add_i32 s16, s16, s22
	v_lshl_add_u64 v[2:3], s[14:15], 0, v[208:209]
	s_mov_b32 m0, s16
	s_nop 0
	global_load_lds_dwordx4 v[2:3], off
	v_lshl_add_u64 v[2:3], s[14:15], 0, v[212:213]
	s_add_i32 m0, s16, 0x2000
	s_nop 0
	global_load_lds_dwordx4 v[2:3], off
	s_waitcnt vmcnt(6)
	s_barrier
	v_mfma_f32_16x16x32_bf16 v[2:5], v[50:53], v[18:21], v[10:13]
	v_mfma_f32_16x16x32_bf16 v[114:117], v[54:57], v[22:25], v[2:5]
	v_mfma_f32_16x16x32_bf16 v[2:5], v[58:61], v[18:21], v[14:17]
	v_mfma_f32_16x16x32_bf16 v[110:113], v[150:153], v[22:25], v[2:5]
	v_mfma_f32_16x16x32_bf16 v[2:5], v[50:53], v[26:29], v[46:49]
	v_mfma_f32_16x16x32_bf16 v[98:101], v[54:57], v[30:33], v[2:5]
	v_mfma_f32_16x16x32_bf16 v[2:5], v[58:61], v[26:29], v[94:97]
	v_mfma_f32_16x16x32_bf16 v[94:97], v[150:153], v[30:33], v[2:5]
	v_mfma_f32_16x16x32_bf16 v[2:5], v[50:53], v[34:37], v[82:85]
	v_mfma_f32_16x16x32_bf16 v[82:85], v[54:57], v[38:41], v[2:5]
	v_mfma_f32_16x16x32_bf16 v[2:5], v[58:61], v[34:37], v[78:81]
	v_mfma_f32_16x16x32_bf16 v[78:81], v[150:153], v[38:41], v[2:5]
	v_mfma_f32_16x16x32_bf16 v[2:5], v[50:53], v[42:45], v[66:69]
	v_mfma_f32_16x16x32_bf16 v[66:69], v[54:57], v[162:165], v[2:5]
	v_mfma_f32_16x16x32_bf16 v[2:5], v[58:61], v[42:45], v[62:65]
	v_mfma_f32_16x16x32_bf16 v[62:65], v[150:153], v[162:165], v[2:5]
	s_add_i32 s64, s64, 2
	s_add_u32 s12, s12, 0x100
	s_addc_u32 s13, s13, 0
	s_add_u32 s62, s62, 0x100
	s_addc_u32 s63, s63, 0
	s_cmp_gt_u32 s64, 13
	s_barrier
	s_cbranch_scc0 .LBB0_491

.LBB0_860:
	s_add_u32 vcc_lo, s12, 0x100
	s_addc_u32 vcc_hi, s13, 0
	s_mov_b32 s8, 0
	s_add_i32 s63, s8, 2
	s_add_u32 s6, s10, 0x100
	s_addc_u32 s7, s11, 0
	s_add_i32 s77, 0, 0x10000
	v_add_u32_e32 v0, s77, v234
	ds_read_b128 v[2:5], v0
	ds_read_b128 v[6:9], v0 offset:1024
	ds_read_b128 v[10:13], v0 offset:2048
	ds_read_b128 v[14:17], v0 offset:3072
	s_cmp_eq_u32 s23, s8
	s_cselect_b32 s8, s38, s6
	s_cselect_b32 s9, s39, s7
	s_cselect_b32 s13, s41, vcc_hi
	s_cselect_b32 s12, s40, vcc_lo
	v_lshl_add_u64 v[50:51], s[10:11], 0, v[214:215]
	s_add_i32 m0, s56, 0xc000
	ds_read_b128 v[18:21], v237
	ds_read_b128 v[22:25], v237 offset:1024
	ds_read_b128 v[26:29], v237 offset:2048
	ds_read_b128 v[30:33], v237 offset:3072
	ds_read_b128 v[34:37], v237 offset:4096
	ds_read_b128 v[38:41], v237 offset:5120
	ds_read_b128 v[42:45], v237 offset:6144
	ds_read_b128 v[46:49], v237 offset:7168
	global_load_lds_dwordx4 v[50:51], off
	v_lshl_add_u64 v[50:51], s[10:11], 0, v[216:217]
	s_add_i32 m0, s56, 0xe000
	s_nop 0
	global_load_lds_dwordx4 v[50:51], off
	s_waitcnt lgkmcnt(8)
	s_barrier
	s_waitcnt lgkmcnt(0)
	v_mfma_f32_16x16x32_bf16 v[154:157], v[2:5], v[34:37], 0
	v_mfma_f32_16x16x32_bf16 v[150:153], v[10:13], v[34:37], 0
	v_mfma_f32_16x16x32_bf16 v[138:141], v[2:5], v[42:45], 0
	v_mfma_f32_16x16x32_bf16 v[134:137], v[10:13], v[42:45], 0
	v_mfma_f32_16x16x32_bf16 v[50:53], v[2:5], v[18:21], 0
	v_mfma_f32_16x16x32_bf16 v[54:57], v[10:13], v[18:21], 0
	v_mfma_f32_16x16x32_bf16 v[58:61], v[2:5], v[26:29], 0
	v_mfma_f32_16x16x32_bf16 v[166:169], v[10:13], v[26:29], 0
	v_mfma_f32_16x16x32_bf16 v[154:157], v[6:9], v[38:41], v[154:157]
	v_mfma_f32_16x16x32_bf16 v[150:153], v[14:17], v[38:41], v[150:153]
	v_mfma_f32_16x16x32_bf16 v[138:141], v[6:9], v[46:49], v[138:141]
	v_mfma_f32_16x16x32_bf16 v[134:137], v[14:17], v[46:49], v[134:137]
	v_mfma_f32_16x16x32_bf16 v[50:53], v[6:9], v[22:25], v[50:53]
	v_mfma_f32_16x16x32_bf16 v[54:57], v[14:17], v[22:25], v[54:57]
	v_mfma_f32_16x16x32_bf16 v[58:61], v[6:9], v[30:33], v[58:61]
	v_mfma_f32_16x16x32_bf16 v[166:169], v[14:17], v[30:33], v[166:169]
	s_barrier
	s_add_i32 s80, 0, 0x14000
	s_add_i32 s10, s77, s53
	v_add_u32_e32 v0, s80, v234
	v_lshl_add_u64 v[222:223], s[12:13], 0, v[208:209]
	s_mov_b32 m0, s10
	ds_read_b128 v[170:173], v0
	ds_read_b128 v[174:177], v0 offset:1024
	ds_read_b128 v[178:181], v0 offset:2048
	ds_read_b128 v[190:193], v0 offset:3072
	global_load_lds_dwordx4 v[222:223], off
	v_lshl_add_u64 v[226:227], s[12:13], 0, v[212:213]
	s_add_i32 m0, s10, 0x2000
	s_nop 0
	global_load_lds_dwordx4 v[226:227], off
	s_barrier
	s_waitcnt lgkmcnt(0)
	v_mfma_f32_16x16x32_bf16 v[186:189], v[170:173], v[18:21], 0
	v_mfma_f32_16x16x32_bf16 v[18:21], v[178:181], v[18:21], 0
	v_mfma_f32_16x16x32_bf16 v[186:189], v[174:177], v[22:25], v[186:189]
	v_mfma_f32_16x16x32_bf16 v[18:21], v[190:193], v[22:25], v[18:21]
	v_mfma_f32_16x16x32_bf16 v[22:25], v[170:173], v[26:29], 0
	v_mfma_f32_16x16x32_bf16 v[26:29], v[178:181], v[26:29], 0
	v_mfma_f32_16x16x32_bf16 v[22:25], v[174:177], v[30:33], v[22:25]
	v_mfma_f32_16x16x32_bf16 v[26:29], v[190:193], v[30:33], v[26:29]
	v_mfma_f32_16x16x32_bf16 v[30:33], v[170:173], v[34:37], 0
	v_mfma_f32_16x16x32_bf16 v[34:37], v[178:181], v[34:37], 0
	v_mfma_f32_16x16x32_bf16 v[30:33], v[174:177], v[38:41], v[30:33]
	v_mfma_f32_16x16x32_bf16 v[34:37], v[190:193], v[38:41], v[34:37]
	v_mfma_f32_16x16x32_bf16 v[38:41], v[170:173], v[42:45], 0
	v_mfma_f32_16x16x32_bf16 v[42:45], v[178:181], v[42:45], 0
	v_mfma_f32_16x16x32_bf16 v[38:41], v[174:177], v[46:49], v[38:41]
	v_mfma_f32_16x16x32_bf16 v[42:45], v[190:193], v[46:49], v[42:45]
	s_mov_b32 m0, s56
	v_lshl_add_u64 v[228:229], s[8:9], 0, v[206:207]
	s_barrier
	ds_read_b128 v[46:49], v237 offset:16384
	ds_read_b128 v[126:129], v237 offset:17408
	ds_read_b128 v[130:133], v237 offset:18432
	ds_read_b128 v[142:145], v237 offset:19456
	ds_read_b128 v[146:149], v237 offset:20480
	ds_read_b128 v[158:161], v237 offset:21504
	ds_read_b128 v[162:165], v237 offset:22528
	ds_read_b128 v[182:185], v237 offset:23552
	global_load_lds_dwordx4 v[228:229], off
	v_lshl_add_u64 v[230:231], s[8:9], 0, v[210:211]
	s_mov_b32 m0, s57
	s_nop 0
	global_load_lds_dwordx4 v[230:231], off
	s_barrier
	s_waitcnt lgkmcnt(0)
	v_mfma_f32_16x16x32_bf16 v[122:125], v[2:5], v[46:49], 0
	v_mfma_f32_16x16x32_bf16 v[118:121], v[10:13], v[46:49], 0
	v_mfma_f32_16x16x32_bf16 v[110:113], v[2:5], v[130:133], 0
	v_mfma_f32_16x16x32_bf16 v[102:105], v[10:13], v[130:133], 0
	v_mfma_f32_16x16x32_bf16 v[94:97], v[2:5], v[146:149], 0
	v_mfma_f32_16x16x32_bf16 v[86:89], v[10:13], v[146:149], 0
	v_mfma_f32_16x16x32_bf16 v[2:5], v[2:5], v[162:165], 0
	v_mfma_f32_16x16x32_bf16 v[122:125], v[6:9], v[126:129], v[122:125]
	v_mfma_f32_16x16x32_bf16 v[118:121], v[14:17], v[126:129], v[118:121]
	v_mfma_f32_16x16x32_bf16 v[110:113], v[6:9], v[142:145], v[110:113]
	v_mfma_f32_16x16x32_bf16 v[102:105], v[14:17], v[142:145], v[102:105]
	v_mfma_f32_16x16x32_bf16 v[94:97], v[6:9], v[158:161], v[94:97]
	v_mfma_f32_16x16x32_bf16 v[86:89], v[14:17], v[158:161], v[86:89]
	v_mfma_f32_16x16x32_bf16 v[2:5], v[6:9], v[182:185], v[2:5]
	v_mfma_f32_16x16x32_bf16 v[6:9], v[10:13], v[162:165], 0
	v_mfma_f32_16x16x32_bf16 v[6:9], v[14:17], v[182:185], v[6:9]
	s_barrier
	s_add_u32 s10, s12, s73
	s_addc_u32 s11, s13, 0
	s_add_i32 s12, s80, s53
	v_lshl_add_u64 v[238:239], s[10:11], 0, v[208:209]
	s_mov_b32 m0, s12
	v_lshl_add_u64 v[240:241], s[10:11], 0, v[212:213]
	global_load_lds_dwordx4 v[238:239], off
	s_add_i32 m0, s12, 0x2000
	s_nop 0
	global_load_lds_dwordx4 v[240:241], off
	s_waitcnt vmcnt(6)
	s_barrier
	v_mfma_f32_16x16x32_bf16 v[70:73], v[178:181], v[130:133], 0
	v_mfma_f32_16x16x32_bf16 v[90:93], v[190:193], v[142:145], v[70:73]
	v_mfma_f32_16x16x32_bf16 v[70:73], v[170:173], v[146:149], 0
	v_mfma_f32_16x16x32_bf16 v[82:85], v[174:177], v[158:161], v[70:73]
	v_mfma_f32_16x16x32_bf16 v[70:73], v[178:181], v[146:149], 0
	v_mfma_f32_16x16x32_bf16 v[66:69], v[170:173], v[162:165], 0
	v_mfma_f32_16x16x32_bf16 v[62:65], v[178:181], v[162:165], 0
	v_mfma_f32_16x16x32_bf16 v[10:13], v[170:173], v[46:49], 0
	v_mfma_f32_16x16x32_bf16 v[14:17], v[178:181], v[46:49], 0
	v_mfma_f32_16x16x32_bf16 v[46:49], v[170:173], v[130:133], 0
	v_mfma_f32_16x16x32_bf16 v[74:77], v[190:193], v[158:161], v[70:73]
	v_mfma_f32_16x16x32_bf16 v[66:69], v[174:177], v[182:185], v[66:69]
	v_mfma_f32_16x16x32_bf16 v[62:65], v[190:193], v[182:185], v[62:65]
	v_mfma_f32_16x16x32_bf16 v[10:13], v[174:177], v[126:129], v[10:13]
	v_mfma_f32_16x16x32_bf16 v[14:17], v[190:193], v[126:129], v[14:17]
	v_mfma_f32_16x16x32_bf16 v[46:49], v[174:177], v[142:145], v[46:49]
	s_add_i32 s10, 0, 0x18000
	v_add_u32_e32 v0, s10, v234
	s_barrier
	ds_read_b128 v[70:73], v0
	ds_read_b128 v[78:81], v0 offset:1024
	ds_read_b128 v[98:101], v0 offset:2048
	ds_read_b128 v[106:109], v0 offset:3072
	s_add_u32 s8, s8, 0xa0000
	s_addc_u32 s9, s9, 0
	s_mov_b32 m0, s58
	v_lshl_add_u64 v[146:147], s[8:9], 0, v[206:207]
	ds_read_b128 v[114:117], v237 offset:32768
	ds_read_b128 v[126:129], v237 offset:33792
	ds_read_b128 v[130:133], v237 offset:34816
	ds_read_b128 v[142:145], v237 offset:35840
	ds_read_b128 v[174:177], v237 offset:36864
	ds_read_b128 v[190:193], v237 offset:37888
	ds_read_b128 v[194:197], v237 offset:38912
	ds_read_b128 v[218:221], v237 offset:39936
	global_load_lds_dwordx4 v[146:147], off
	v_lshl_add_u64 v[146:147], s[8:9], 0, v[210:211]
	s_mov_b32 m0, s59
	s_nop 0
	global_load_lds_dwordx4 v[146:147], off
	s_waitcnt lgkmcnt(8)
	s_barrier
	s_waitcnt lgkmcnt(0)
	v_mfma_f32_16x16x32_bf16 v[50:53], v[70:73], v[114:117], v[50:53]
	v_mfma_f32_16x16x32_bf16 v[202:205], v[78:81], v[126:129], v[50:53]
	v_mfma_f32_16x16x32_bf16 v[50:53], v[98:101], v[114:117], v[54:57]
	v_mfma_f32_16x16x32_bf16 v[198:201], v[106:109], v[126:129], v[50:53]
	v_mfma_f32_16x16x32_bf16 v[50:53], v[70:73], v[130:133], v[58:61]
	v_mfma_f32_16x16x32_bf16 v[178:181], v[78:81], v[142:145], v[50:53]
	v_mfma_f32_16x16x32_bf16 v[50:53], v[98:101], v[130:133], v[166:169]
	v_mfma_f32_16x16x32_bf16 v[170:173], v[106:109], v[142:145], v[50:53]
	v_mfma_f32_16x16x32_bf16 v[50:53], v[70:73], v[174:177], v[154:157]
	v_mfma_f32_16x16x32_bf16 v[154:157], v[78:81], v[190:193], v[50:53]
	v_mfma_f32_16x16x32_bf16 v[50:53], v[98:101], v[174:177], v[150:153]
	v_mfma_f32_16x16x32_bf16 v[150:153], v[106:109], v[190:193], v[50:53]
	v_mfma_f32_16x16x32_bf16 v[50:53], v[70:73], v[194:197], v[138:141]
	v_mfma_f32_16x16x32_bf16 v[138:141], v[78:81], v[218:221], v[50:53]
	v_mfma_f32_16x16x32_bf16 v[50:53], v[98:101], v[194:197], v[134:137]
	v_mfma_f32_16x16x32_bf16 v[134:137], v[106:109], v[218:221], v[50:53]
	s_barrier
	s_add_i32 s8, 0, 0x1c000
	s_add_i32 s9, s10, s53
	v_add_u32_e32 v0, s8, v234
	v_lshl_add_u64 v[146:147], v[222:223], 0, s[20:21]
	s_mov_b32 m0, s9
	ds_read_b128 v[50:53], v0
	ds_read_b128 v[54:57], v0 offset:1024
	ds_read_b128 v[58:61], v0 offset:2048
	ds_read_b128 v[166:169], v0 offset:3072
	global_load_lds_dwordx4 v[146:147], off
	v_lshl_add_u64 v[146:147], v[226:227], 0, s[20:21]
	s_add_i32 m0, s9, 0x2000
	s_nop 0
	global_load_lds_dwordx4 v[146:147], off
	s_barrier
	s_waitcnt lgkmcnt(0)
	v_mfma_f32_16x16x32_bf16 v[18:21], v[58:61], v[114:117], v[18:21]
	v_mfma_f32_16x16x32_bf16 v[182:185], v[166:169], v[126:129], v[18:21]
	v_mfma_f32_16x16x32_bf16 v[18:21], v[50:53], v[130:133], v[22:25]
	v_mfma_f32_16x16x32_bf16 v[162:165], v[54:57], v[142:145], v[18:21]
	v_mfma_f32_16x16x32_bf16 v[18:21], v[58:61], v[130:133], v[26:29]
	v_mfma_f32_16x16x32_bf16 v[146:149], v[50:53], v[114:117], v[186:189]
	v_mfma_f32_16x16x32_bf16 v[158:161], v[166:169], v[142:145], v[18:21]
	v_mfma_f32_16x16x32_bf16 v[18:21], v[50:53], v[174:177], v[30:33]
	v_mfma_f32_16x16x32_bf16 v[186:189], v[54:57], v[126:129], v[146:149]
	v_mfma_f32_16x16x32_bf16 v[146:149], v[54:57], v[190:193], v[18:21]
	v_mfma_f32_16x16x32_bf16 v[18:21], v[58:61], v[174:177], v[34:37]
	v_mfma_f32_16x16x32_bf16 v[142:145], v[166:169], v[190:193], v[18:21]
	v_mfma_f32_16x16x32_bf16 v[18:21], v[50:53], v[194:197], v[38:41]
	v_mfma_f32_16x16x32_bf16 v[130:133], v[54:57], v[218:221], v[18:21]
	v_mfma_f32_16x16x32_bf16 v[18:21], v[58:61], v[194:197], v[42:45]
	v_mfma_f32_16x16x32_bf16 v[126:129], v[166:169], v[218:221], v[18:21]
	s_mov_b32 m0, s72
	v_lshl_add_u64 v[114:115], v[228:229], 0, s[20:21]
	s_barrier
	s_nop 2
	ds_read_b128 v[18:21], v237 offset:49152
	ds_read_b128 v[22:25], v237 offset:50176
	ds_read_b128 v[26:29], v237 offset:51200
	ds_read_b128 v[30:33], v237 offset:52224
	ds_read_b128 v[34:37], v237 offset:53248
	ds_read_b128 v[38:41], v237 offset:54272
	ds_read_b128 v[42:45], v237 offset:55296
	ds_read_b128 v[174:177], v237 offset:56320
	global_load_lds_dwordx4 v[114:115], off
	v_lshl_add_u64 v[114:115], v[230:231], 0, s[20:21]
	s_mov_b32 m0, s22
	s_nop 0
	global_load_lds_dwordx4 v[114:115], off
	s_barrier
	s_waitcnt lgkmcnt(0)
	v_mfma_f32_16x16x32_bf16 v[114:117], v[70:73], v[18:21], v[122:125]
	v_mfma_f32_16x16x32_bf16 v[110:113], v[70:73], v[26:29], v[110:113]
	v_mfma_f32_16x16x32_bf16 v[94:97], v[70:73], v[34:37], v[94:97]
	v_mfma_f32_16x16x32_bf16 v[2:5], v[70:73], v[42:45], v[2:5]
	v_mfma_f32_16x16x32_bf16 v[122:125], v[78:81], v[22:25], v[114:117]
	v_mfma_f32_16x16x32_bf16 v[114:117], v[98:101], v[18:21], v[118:121]
	v_mfma_f32_16x16x32_bf16 v[110:113], v[78:81], v[30:33], v[110:113]
	v_mfma_f32_16x16x32_bf16 v[102:105], v[98:101], v[26:29], v[102:105]
	v_mfma_f32_16x16x32_bf16 v[94:97], v[78:81], v[38:41], v[94:97]
	v_mfma_f32_16x16x32_bf16 v[86:89], v[98:101], v[34:37], v[86:89]
	v_mfma_f32_16x16x32_bf16 v[78:81], v[78:81], v[174:177], v[2:5]
	v_mfma_f32_16x16x32_bf16 v[2:5], v[98:101], v[42:45], v[6:9]
	v_mfma_f32_16x16x32_bf16 v[118:121], v[106:109], v[22:25], v[114:117]
	v_mfma_f32_16x16x32_bf16 v[102:105], v[106:109], v[30:33], v[102:105]
	v_mfma_f32_16x16x32_bf16 v[86:89], v[106:109], v[38:41], v[86:89]
	v_mfma_f32_16x16x32_bf16 v[70:73], v[106:109], v[174:177], v[2:5]
	s_barrier
	s_add_i32 s8, s8, s53
	s_nop 0
	v_lshl_add_u64 v[2:3], v[238:239], 0, s[20:21]
	s_mov_b32 m0, s8
	s_nop 0
	global_load_lds_dwordx4 v[2:3], off
	v_lshl_add_u64 v[2:3], v[240:241], 0, s[20:21]
	s_add_i32 m0, s8, 0x2000
	s_nop 0
	global_load_lds_dwordx4 v[2:3], off
	s_waitcnt vmcnt(6)
	s_barrier
	v_mfma_f32_16x16x32_bf16 v[2:5], v[50:53], v[18:21], v[10:13]
	v_mfma_f32_16x16x32_bf16 v[114:117], v[54:57], v[22:25], v[2:5]
	v_mfma_f32_16x16x32_bf16 v[2:5], v[58:61], v[18:21], v[14:17]
	v_mfma_f32_16x16x32_bf16 v[106:109], v[166:169], v[22:25], v[2:5]
	v_mfma_f32_16x16x32_bf16 v[2:5], v[50:53], v[26:29], v[46:49]
	v_mfma_f32_16x16x32_bf16 v[98:101], v[54:57], v[30:33], v[2:5]
	v_mfma_f32_16x16x32_bf16 v[2:5], v[58:61], v[26:29], v[90:93]
	v_mfma_f32_16x16x32_bf16 v[90:93], v[166:169], v[30:33], v[2:5]
	v_mfma_f32_16x16x32_bf16 v[2:5], v[50:53], v[34:37], v[82:85]
	v_mfma_f32_16x16x32_bf16 v[82:85], v[54:57], v[38:41], v[2:5]
	v_mfma_f32_16x16x32_bf16 v[2:5], v[58:61], v[34:37], v[74:77]
	v_mfma_f32_16x16x32_bf16 v[74:77], v[166:169], v[38:41], v[2:5]
	v_mfma_f32_16x16x32_bf16 v[2:5], v[50:53], v[42:45], v[66:69]
	v_mfma_f32_16x16x32_bf16 v[66:69], v[54:57], v[174:177], v[2:5]
	v_mfma_f32_16x16x32_bf16 v[2:5], v[58:61], v[42:45], v[62:65]
	v_mfma_f32_16x16x32_bf16 v[62:65], v[166:169], v[174:177], v[2:5]
	s_add_u32 vcc_lo, vcc_lo, 0x100
	s_addc_u32 vcc_hi, vcc_hi, 0
	s_cmp_ge_u32 s63, s91
	s_mov_b64 s[10:11], s[6:7]
	s_mov_b32 s8, s63
	s_barrier
	s_cbranch_scc0 .LBB0_861
	s_branch .Lpeel_exit_g2
.LBB0_861:
	s_add_i32 s63, s8, 2
	s_add_u32 s6, s10, 0x100
	s_addc_u32 s7, s11, 0
	s_add_i32 s77, 0, 0x10000
	v_add_u32_e32 v0, s77, v234
	ds_read_b128 v[2:5], v0
	ds_read_b128 v[6:9], v0 offset:1024
	ds_read_b128 v[10:13], v0 offset:2048
	ds_read_b128 v[14:17], v0 offset:3072
	s_cmp_eq_u32 s23, s8
	s_cselect_b32 s8, s38, s6
	s_cselect_b32 s9, s39, s7
	s_cselect_b32 s13, s41, vcc_hi
	s_cselect_b32 s12, s40, vcc_lo
	v_lshl_add_u64 v[50:51], s[10:11], 0, v[214:215]
	s_add_i32 m0, s56, 0xc000
	ds_read_b128 v[18:21], v237
	ds_read_b128 v[22:25], v237 offset:1024
	ds_read_b128 v[26:29], v237 offset:2048
	ds_read_b128 v[30:33], v237 offset:3072
	ds_read_b128 v[34:37], v237 offset:4096
	ds_read_b128 v[38:41], v237 offset:5120
	ds_read_b128 v[42:45], v237 offset:6144
	ds_read_b128 v[46:49], v237 offset:7168
	global_load_lds_dwordx4 v[50:51], off
	v_lshl_add_u64 v[50:51], s[10:11], 0, v[216:217]
	s_add_i32 m0, s56, 0xe000
	s_nop 0
	global_load_lds_dwordx4 v[50:51], off
	s_waitcnt lgkmcnt(8)
	s_barrier
	s_waitcnt lgkmcnt(0)
	v_mfma_f32_16x16x32_bf16 v[154:157], v[2:5], v[34:37], v[154:157]
	v_mfma_f32_16x16x32_bf16 v[150:153], v[10:13], v[34:37], v[150:153]
	v_mfma_f32_16x16x32_bf16 v[138:141], v[2:5], v[42:45], v[138:141]
	v_mfma_f32_16x16x32_bf16 v[134:137], v[10:13], v[42:45], v[134:137]
	v_mfma_f32_16x16x32_bf16 v[50:53], v[2:5], v[18:21], v[202:205]
	v_mfma_f32_16x16x32_bf16 v[54:57], v[10:13], v[18:21], v[198:201]
	v_mfma_f32_16x16x32_bf16 v[58:61], v[2:5], v[26:29], v[178:181]
	v_mfma_f32_16x16x32_bf16 v[166:169], v[10:13], v[26:29], v[170:173]
	v_mfma_f32_16x16x32_bf16 v[154:157], v[6:9], v[38:41], v[154:157]
	v_mfma_f32_16x16x32_bf16 v[150:153], v[14:17], v[38:41], v[150:153]
	v_mfma_f32_16x16x32_bf16 v[138:141], v[6:9], v[46:49], v[138:141]
	v_mfma_f32_16x16x32_bf16 v[134:137], v[14:17], v[46:49], v[134:137]
	v_mfma_f32_16x16x32_bf16 v[50:53], v[6:9], v[22:25], v[50:53]
	v_mfma_f32_16x16x32_bf16 v[54:57], v[14:17], v[22:25], v[54:57]
	v_mfma_f32_16x16x32_bf16 v[58:61], v[6:9], v[30:33], v[58:61]
	v_mfma_f32_16x16x32_bf16 v[166:169], v[14:17], v[30:33], v[166:169]
	s_barrier
	s_add_i32 s80, 0, 0x14000
	s_add_i32 s10, s77, s53
	v_add_u32_e32 v0, s80, v234
	v_lshl_add_u64 v[222:223], s[12:13], 0, v[208:209]
	s_mov_b32 m0, s10
	ds_read_b128 v[170:173], v0
	ds_read_b128 v[174:177], v0 offset:1024
	ds_read_b128 v[178:181], v0 offset:2048
	ds_read_b128 v[190:193], v0 offset:3072
	global_load_lds_dwordx4 v[222:223], off
	v_lshl_add_u64 v[226:227], s[12:13], 0, v[212:213]
	s_add_i32 m0, s10, 0x2000
	s_nop 0
	global_load_lds_dwordx4 v[226:227], off
	s_barrier
	s_waitcnt lgkmcnt(0)
	v_mfma_f32_16x16x32_bf16 v[186:189], v[170:173], v[18:21], v[186:189]
	v_mfma_f32_16x16x32_bf16 v[18:21], v[178:181], v[18:21], v[182:185]
	v_mfma_f32_16x16x32_bf16 v[186:189], v[174:177], v[22:25], v[186:189]
	v_mfma_f32_16x16x32_bf16 v[18:21], v[190:193], v[22:25], v[18:21]
	v_mfma_f32_16x16x32_bf16 v[22:25], v[170:173], v[26:29], v[162:165]
	v_mfma_f32_16x16x32_bf16 v[26:29], v[178:181], v[26:29], v[158:161]
	v_mfma_f32_16x16x32_bf16 v[22:25], v[174:177], v[30:33], v[22:25]
	v_mfma_f32_16x16x32_bf16 v[26:29], v[190:193], v[30:33], v[26:29]
	v_mfma_f32_16x16x32_bf16 v[30:33], v[170:173], v[34:37], v[146:149]
	v_mfma_f32_16x16x32_bf16 v[34:37], v[178:181], v[34:37], v[142:145]
	v_mfma_f32_16x16x32_bf16 v[30:33], v[174:177], v[38:41], v[30:33]
	v_mfma_f32_16x16x32_bf16 v[34:37], v[190:193], v[38:41], v[34:37]
	v_mfma_f32_16x16x32_bf16 v[38:41], v[170:173], v[42:45], v[130:133]
	v_mfma_f32_16x16x32_bf16 v[42:45], v[178:181], v[42:45], v[126:129]
	v_mfma_f32_16x16x32_bf16 v[38:41], v[174:177], v[46:49], v[38:41]
	v_mfma_f32_16x16x32_bf16 v[42:45], v[190:193], v[46:49], v[42:45]
	s_mov_b32 m0, s56
	v_lshl_add_u64 v[228:229], s[8:9], 0, v[206:207]
	s_barrier
	ds_read_b128 v[46:49], v237 offset:16384
	ds_read_b128 v[126:129], v237 offset:17408
	ds_read_b128 v[130:133], v237 offset:18432
	ds_read_b128 v[142:145], v237 offset:19456
	ds_read_b128 v[146:149], v237 offset:20480
	ds_read_b128 v[158:161], v237 offset:21504
	ds_read_b128 v[162:165], v237 offset:22528
	ds_read_b128 v[182:185], v237 offset:23552
	global_load_lds_dwordx4 v[228:229], off
	v_lshl_add_u64 v[230:231], s[8:9], 0, v[210:211]
	s_mov_b32 m0, s57
	s_nop 0
	global_load_lds_dwordx4 v[230:231], off
	s_barrier
	s_waitcnt lgkmcnt(0)
	v_mfma_f32_16x16x32_bf16 v[122:125], v[2:5], v[46:49], v[122:125]
	v_mfma_f32_16x16x32_bf16 v[118:121], v[10:13], v[46:49], v[118:121]
	v_mfma_f32_16x16x32_bf16 v[110:113], v[2:5], v[130:133], v[110:113]
	v_mfma_f32_16x16x32_bf16 v[102:105], v[10:13], v[130:133], v[102:105]
	v_mfma_f32_16x16x32_bf16 v[94:97], v[2:5], v[146:149], v[94:97]
	v_mfma_f32_16x16x32_bf16 v[86:89], v[10:13], v[146:149], v[86:89]
	v_mfma_f32_16x16x32_bf16 v[2:5], v[2:5], v[162:165], v[78:81]
	v_mfma_f32_16x16x32_bf16 v[122:125], v[6:9], v[126:129], v[122:125]
	v_mfma_f32_16x16x32_bf16 v[118:121], v[14:17], v[126:129], v[118:121]
	v_mfma_f32_16x16x32_bf16 v[110:113], v[6:9], v[142:145], v[110:113]
	v_mfma_f32_16x16x32_bf16 v[102:105], v[14:17], v[142:145], v[102:105]
	v_mfma_f32_16x16x32_bf16 v[94:97], v[6:9], v[158:161], v[94:97]
	v_mfma_f32_16x16x32_bf16 v[86:89], v[14:17], v[158:161], v[86:89]
	v_mfma_f32_16x16x32_bf16 v[2:5], v[6:9], v[182:185], v[2:5]
	v_mfma_f32_16x16x32_bf16 v[6:9], v[10:13], v[162:165], v[70:73]
	v_mfma_f32_16x16x32_bf16 v[6:9], v[14:17], v[182:185], v[6:9]
	s_barrier
	s_add_u32 s10, s12, s73
	s_addc_u32 s11, s13, 0
	s_add_i32 s12, s80, s53
	v_lshl_add_u64 v[238:239], s[10:11], 0, v[208:209]
	s_mov_b32 m0, s12
	v_lshl_add_u64 v[240:241], s[10:11], 0, v[212:213]
	global_load_lds_dwordx4 v[238:239], off
	s_add_i32 m0, s12, 0x2000
	s_nop 0
	global_load_lds_dwordx4 v[240:241], off
	s_waitcnt vmcnt(6)
	s_barrier
	v_mfma_f32_16x16x32_bf16 v[70:73], v[178:181], v[130:133], v[90:93]
	v_mfma_f32_16x16x32_bf16 v[90:93], v[190:193], v[142:145], v[70:73]
	v_mfma_f32_16x16x32_bf16 v[70:73], v[170:173], v[146:149], v[82:85]
	v_mfma_f32_16x16x32_bf16 v[82:85], v[174:177], v[158:161], v[70:73]
	v_mfma_f32_16x16x32_bf16 v[70:73], v[178:181], v[146:149], v[74:77]
	v_mfma_f32_16x16x32_bf16 v[66:69], v[170:173], v[162:165], v[66:69]
	v_mfma_f32_16x16x32_bf16 v[62:65], v[178:181], v[162:165], v[62:65]
	v_mfma_f32_16x16x32_bf16 v[10:13], v[170:173], v[46:49], v[114:117]
	v_mfma_f32_16x16x32_bf16 v[14:17], v[178:181], v[46:49], v[106:109]
	v_mfma_f32_16x16x32_bf16 v[46:49], v[170:173], v[130:133], v[98:101]
	v_mfma_f32_16x16x32_bf16 v[74:77], v[190:193], v[158:161], v[70:73]
	v_mfma_f32_16x16x32_bf16 v[66:69], v[174:177], v[182:185], v[66:69]
	v_mfma_f32_16x16x32_bf16 v[62:65], v[190:193], v[182:185], v[62:65]
	v_mfma_f32_16x16x32_bf16 v[10:13], v[174:177], v[126:129], v[10:13]
	v_mfma_f32_16x16x32_bf16 v[14:17], v[190:193], v[126:129], v[14:17]
	v_mfma_f32_16x16x32_bf16 v[46:49], v[174:177], v[142:145], v[46:49]
	s_add_i32 s10, 0, 0x18000
	v_add_u32_e32 v0, s10, v234
	s_barrier
	ds_read_b128 v[70:73], v0
	ds_read_b128 v[78:81], v0 offset:1024
	ds_read_b128 v[98:101], v0 offset:2048
	ds_read_b128 v[106:109], v0 offset:3072
	s_add_u32 s8, s8, 0xa0000
	s_addc_u32 s9, s9, 0
	s_mov_b32 m0, s58
	v_lshl_add_u64 v[146:147], s[8:9], 0, v[206:207]
	ds_read_b128 v[114:117], v237 offset:32768
	ds_read_b128 v[126:129], v237 offset:33792
	ds_read_b128 v[130:133], v237 offset:34816
	ds_read_b128 v[142:145], v237 offset:35840
	ds_read_b128 v[174:177], v237 offset:36864
	ds_read_b128 v[190:193], v237 offset:37888
	ds_read_b128 v[194:197], v237 offset:38912
	ds_read_b128 v[218:221], v237 offset:39936
	global_load_lds_dwordx4 v[146:147], off
	v_lshl_add_u64 v[146:147], s[8:9], 0, v[210:211]
	s_mov_b32 m0, s59
	s_nop 0
	global_load_lds_dwordx4 v[146:147], off
	s_waitcnt lgkmcnt(8)
	s_barrier
	s_waitcnt lgkmcnt(0)
	v_mfma_f32_16x16x32_bf16 v[50:53], v[70:73], v[114:117], v[50:53]
	v_mfma_f32_16x16x32_bf16 v[202:205], v[78:81], v[126:129], v[50:53]
	v_mfma_f32_16x16x32_bf16 v[50:53], v[98:101], v[114:117], v[54:57]
	v_mfma_f32_16x16x32_bf16 v[198:201], v[106:109], v[126:129], v[50:53]
	v_mfma_f32_16x16x32_bf16 v[50:53], v[70:73], v[130:133], v[58:61]
	v_mfma_f32_16x16x32_bf16 v[178:181], v[78:81], v[142:145], v[50:53]
	v_mfma_f32_16x16x32_bf16 v[50:53], v[98:101], v[130:133], v[166:169]
	v_mfma_f32_16x16x32_bf16 v[170:173], v[106:109], v[142:145], v[50:53]
	v_mfma_f32_16x16x32_bf16 v[50:53], v[70:73], v[174:177], v[154:157]
	v_mfma_f32_16x16x32_bf16 v[154:157], v[78:81], v[190:193], v[50:53]
	v_mfma_f32_16x16x32_bf16 v[50:53], v[98:101], v[174:177], v[150:153]
	v_mfma_f32_16x16x32_bf16 v[150:153], v[106:109], v[190:193], v[50:53]
	v_mfma_f32_16x16x32_bf16 v[50:53], v[70:73], v[194:197], v[138:141]
	v_mfma_f32_16x16x32_bf16 v[138:141], v[78:81], v[218:221], v[50:53]
	v_mfma_f32_16x16x32_bf16 v[50:53], v[98:101], v[194:197], v[134:137]
	v_mfma_f32_16x16x32_bf16 v[134:137], v[106:109], v[218:221], v[50:53]
	s_barrier
	s_add_i32 s8, 0, 0x1c000
	s_add_i32 s9, s10, s53
	v_add_u32_e32 v0, s8, v234
	v_lshl_add_u64 v[146:147], v[222:223], 0, s[20:21]
	s_mov_b32 m0, s9
	ds_read_b128 v[50:53], v0
	ds_read_b128 v[54:57], v0 offset:1024
	ds_read_b128 v[58:61], v0 offset:2048
	ds_read_b128 v[166:169], v0 offset:3072
	global_load_lds_dwordx4 v[146:147], off
	v_lshl_add_u64 v[146:147], v[226:227], 0, s[20:21]
	s_add_i32 m0, s9, 0x2000
	s_nop 0
	global_load_lds_dwordx4 v[146:147], off
	s_barrier
	s_waitcnt lgkmcnt(0)
	v_mfma_f32_16x16x32_bf16 v[18:21], v[58:61], v[114:117], v[18:21]
	v_mfma_f32_16x16x32_bf16 v[182:185], v[166:169], v[126:129], v[18:21]
	v_mfma_f32_16x16x32_bf16 v[18:21], v[50:53], v[130:133], v[22:25]
	v_mfma_f32_16x16x32_bf16 v[162:165], v[54:57], v[142:145], v[18:21]
	v_mfma_f32_16x16x32_bf16 v[18:21], v[58:61], v[130:133], v[26:29]
	v_mfma_f32_16x16x32_bf16 v[146:149], v[50:53], v[114:117], v[186:189]
	v_mfma_f32_16x16x32_bf16 v[158:161], v[166:169], v[142:145], v[18:21]
	v_mfma_f32_16x16x32_bf16 v[18:21], v[50:53], v[174:177], v[30:33]
	v_mfma_f32_16x16x32_bf16 v[186:189], v[54:57], v[126:129], v[146:149]
	v_mfma_f32_16x16x32_bf16 v[146:149], v[54:57], v[190:193], v[18:21]
	v_mfma_f32_16x16x32_bf16 v[18:21], v[58:61], v[174:177], v[34:37]
	v_mfma_f32_16x16x32_bf16 v[142:145], v[166:169], v[190:193], v[18:21]
	v_mfma_f32_16x16x32_bf16 v[18:21], v[50:53], v[194:197], v[38:41]
	v_mfma_f32_16x16x32_bf16 v[130:133], v[54:57], v[218:221], v[18:21]
	v_mfma_f32_16x16x32_bf16 v[18:21], v[58:61], v[194:197], v[42:45]
	v_mfma_f32_16x16x32_bf16 v[126:129], v[166:169], v[218:221], v[18:21]
	s_mov_b32 m0, s72
	v_lshl_add_u64 v[114:115], v[228:229], 0, s[20:21]
	s_barrier
	s_nop 2
	ds_read_b128 v[18:21], v237 offset:49152
	ds_read_b128 v[22:25], v237 offset:50176
	ds_read_b128 v[26:29], v237 offset:51200
	ds_read_b128 v[30:33], v237 offset:52224
	ds_read_b128 v[34:37], v237 offset:53248
	ds_read_b128 v[38:41], v237 offset:54272
	ds_read_b128 v[42:45], v237 offset:55296
	ds_read_b128 v[174:177], v237 offset:56320
	global_load_lds_dwordx4 v[114:115], off
	v_lshl_add_u64 v[114:115], v[230:231], 0, s[20:21]
	s_mov_b32 m0, s22
	s_nop 0
	global_load_lds_dwordx4 v[114:115], off
	s_barrier
	s_waitcnt lgkmcnt(0)
	v_mfma_f32_16x16x32_bf16 v[114:117], v[70:73], v[18:21], v[122:125]
	v_mfma_f32_16x16x32_bf16 v[110:113], v[70:73], v[26:29], v[110:113]
	v_mfma_f32_16x16x32_bf16 v[94:97], v[70:73], v[34:37], v[94:97]
	v_mfma_f32_16x16x32_bf16 v[2:5], v[70:73], v[42:45], v[2:5]
	v_mfma_f32_16x16x32_bf16 v[122:125], v[78:81], v[22:25], v[114:117]
	v_mfma_f32_16x16x32_bf16 v[114:117], v[98:101], v[18:21], v[118:121]
	v_mfma_f32_16x16x32_bf16 v[110:113], v[78:81], v[30:33], v[110:113]
	v_mfma_f32_16x16x32_bf16 v[102:105], v[98:101], v[26:29], v[102:105]
	v_mfma_f32_16x16x32_bf16 v[94:97], v[78:81], v[38:41], v[94:97]
	v_mfma_f32_16x16x32_bf16 v[86:89], v[98:101], v[34:37], v[86:89]
	v_mfma_f32_16x16x32_bf16 v[78:81], v[78:81], v[174:177], v[2:5]
	v_mfma_f32_16x16x32_bf16 v[2:5], v[98:101], v[42:45], v[6:9]
	v_mfma_f32_16x16x32_bf16 v[118:121], v[106:109], v[22:25], v[114:117]
	v_mfma_f32_16x16x32_bf16 v[102:105], v[106:109], v[30:33], v[102:105]
	v_mfma_f32_16x16x32_bf16 v[86:89], v[106:109], v[38:41], v[86:89]
	v_mfma_f32_16x16x32_bf16 v[70:73], v[106:109], v[174:177], v[2:5]
	s_barrier
	s_add_i32 s8, s8, s53
	s_nop 0
	v_lshl_add_u64 v[2:3], v[238:239], 0, s[20:21]
	s_mov_b32 m0, s8
	s_nop 0
	global_load_lds_dwordx4 v[2:3], off
	v_lshl_add_u64 v[2:3], v[240:241], 0, s[20:21]
	s_add_i32 m0, s8, 0x2000
	s_nop 0
	global_load_lds_dwordx4 v[2:3], off
	s_waitcnt vmcnt(6)
	s_barrier
	v_mfma_f32_16x16x32_bf16 v[2:5], v[50:53], v[18:21], v[10:13]
	v_mfma_f32_16x16x32_bf16 v[114:117], v[54:57], v[22:25], v[2:5]
	v_mfma_f32_16x16x32_bf16 v[2:5], v[58:61], v[18:21], v[14:17]
	v_mfma_f32_16x16x32_bf16 v[106:109], v[166:169], v[22:25], v[2:5]
	v_mfma_f32_16x16x32_bf16 v[2:5], v[50:53], v[26:29], v[46:49]
	v_mfma_f32_16x16x32_bf16 v[98:101], v[54:57], v[30:33], v[2:5]
	v_mfma_f32_16x16x32_bf16 v[2:5], v[58:61], v[26:29], v[90:93]
	v_mfma_f32_16x16x32_bf16 v[90:93], v[166:169], v[30:33], v[2:5]
	v_mfma_f32_16x16x32_bf16 v[2:5], v[50:53], v[34:37], v[82:85]
	v_mfma_f32_16x16x32_bf16 v[82:85], v[54:57], v[38:41], v[2:5]
	v_mfma_f32_16x16x32_bf16 v[2:5], v[58:61], v[34:37], v[74:77]
	v_mfma_f32_16x16x32_bf16 v[74:77], v[166:169], v[38:41], v[2:5]
	v_mfma_f32_16x16x32_bf16 v[2:5], v[50:53], v[42:45], v[66:69]
	v_mfma_f32_16x16x32_bf16 v[66:69], v[54:57], v[174:177], v[2:5]
	v_mfma_f32_16x16x32_bf16 v[2:5], v[58:61], v[42:45], v[62:65]
	v_mfma_f32_16x16x32_bf16 v[62:65], v[166:169], v[174:177], v[2:5]
	s_add_u32 vcc_lo, vcc_lo, 0x100
	s_addc_u32 vcc_hi, vcc_hi, 0
	s_cmp_ge_u32 s63, s91
	s_mov_b64 s[10:11], s[6:7]
	s_mov_b32 s8, s63
	s_barrier
	s_cbranch_scc0 .LBB0_861

.LBB0_1151:
	v_mov_b64_e32 v[2:3], 0x200
	s_ashr_i32 s13, s12, 31
	v_cmp_lt_i64_e32 vcc, s[14:15], v[2:3]
	s_lshl_b64 s[14:15], s[12:13], 19
	s_add_u32 s14, s80, s14
	s_addc_u32 s15, s83, s15
	s_and_b64 s[16:17], vcc, exec
	s_cselect_b32 s13, s15, s7
	s_cselect_b32 s54, s14, s6
	s_ashr_i32 s11, s10, 31
	s_lshl_b64 s[16:17], s[10:11], 19
	s_add_u32 s16, s23, s16
	s_addc_u32 s17, s36, s17
	s_and_b64 s[26:27], vcc, exec
	s_cselect_b32 s11, s17, s9
	s_cselect_b32 s55, s16, s8
	s_add_u32 s6, s6, 0x40080
	s_addc_u32 s7, s7, 0
	s_add_u32 s56, s8, 0x100
	s_addc_u32 s57, s9, 0
	s_mov_b32 s58, -2
	s_add_u32 s8, s6, 0xfffc0080
	s_addc_u32 s9, s7, -1
	s_add_i32 s59, 0, 0x10000
	v_add_u32_e32 v0, s59, v249
	ds_read_b128 v[2:5], v0
	ds_read_b128 v[6:9], v0 offset:1024
	ds_read_b128 v[10:13], v0 offset:2048
	ds_read_b128 v[14:17], v0 offset:3072
	s_cmp_eq_u32 s58, 12
	s_cselect_b32 s27, s13, s9
	s_cselect_b32 s26, s54, s8
	s_cselect_b32 s9, s11, s57
	s_cselect_b32 s8, s55, s56
	v_lshl_add_u64 v[50:51], s[6:7], 0, v[234:235]
	s_add_i32 m0, s38, 0xc000
	ds_read_b128 v[18:21], v222
	ds_read_b128 v[22:25], v222 offset:1024
	ds_read_b128 v[26:29], v222 offset:2048
	ds_read_b128 v[30:33], v222 offset:3072
	ds_read_b128 v[34:37], v222 offset:4096
	ds_read_b128 v[38:41], v222 offset:5120
	ds_read_b128 v[42:45], v222 offset:6144
	ds_read_b128 v[46:49], v222 offset:7168
	global_load_lds_dwordx4 v[50:51], off
	v_lshl_add_u64 v[50:51], s[6:7], 0, v[236:237]
	s_add_i32 m0, s38, 0xe000
	s_nop 0
	global_load_lds_dwordx4 v[50:51], off
	s_waitcnt lgkmcnt(8)
	s_barrier
	s_waitcnt lgkmcnt(0)
	v_mfma_f32_16x16x32_bf16 v[150:153], v[10:13], v[42:45], 0
	v_mfma_f32_16x16x32_bf16 v[50:53], v[2:5], v[18:21], 0
	v_mfma_f32_16x16x32_bf16 v[54:57], v[10:13], v[18:21], 0
	v_mfma_f32_16x16x32_bf16 v[58:61], v[2:5], v[26:29], 0
	v_mfma_f32_16x16x32_bf16 v[62:65], v[10:13], v[26:29], 0
	v_mfma_f32_16x16x32_bf16 v[66:69], v[2:5], v[34:37], 0
	v_mfma_f32_16x16x32_bf16 v[70:73], v[10:13], v[34:37], 0
	v_mfma_f32_16x16x32_bf16 v[74:77], v[2:5], v[42:45], 0
	v_mfma_f32_16x16x32_bf16 v[150:153], v[14:17], v[46:49], v[150:153]
	v_mfma_f32_16x16x32_bf16 v[50:53], v[6:9], v[22:25], v[50:53]
	v_mfma_f32_16x16x32_bf16 v[54:57], v[14:17], v[22:25], v[54:57]
	v_mfma_f32_16x16x32_bf16 v[58:61], v[6:9], v[30:33], v[58:61]
	v_mfma_f32_16x16x32_bf16 v[62:65], v[14:17], v[30:33], v[62:65]
	v_mfma_f32_16x16x32_bf16 v[66:69], v[6:9], v[38:41], v[66:69]
	v_mfma_f32_16x16x32_bf16 v[70:73], v[14:17], v[38:41], v[70:73]
	v_mfma_f32_16x16x32_bf16 v[74:77], v[6:9], v[46:49], v[74:77]
	s_barrier
	s_add_i32 s64, 0, 0x14000
	s_add_i32 s59, s59, s37
	v_add_u32_e32 v0, s64, v249
	v_lshl_add_u64 v[238:239], s[8:9], 0, v[230:231]
	s_mov_b32 m0, s59
	ds_read_b128 v[154:157], v0
	ds_read_b128 v[166:169], v0 offset:1024
	ds_read_b128 v[170:173], v0 offset:2048
	ds_read_b128 v[182:185], v0 offset:3072
	global_load_lds_dwordx4 v[238:239], off
	v_lshl_add_u64 v[240:241], s[8:9], 0, v[226:227]
	s_add_i32 m0, s59, 0x2000
	s_nop 0
	global_load_lds_dwordx4 v[240:241], off
	s_barrier
	s_waitcnt lgkmcnt(0)
	v_mfma_f32_16x16x32_bf16 v[186:189], v[154:157], v[18:21], 0
	v_mfma_f32_16x16x32_bf16 v[18:21], v[170:173], v[18:21], 0
	v_mfma_f32_16x16x32_bf16 v[194:197], v[166:169], v[22:25], v[186:189]
	v_mfma_f32_16x16x32_bf16 v[18:21], v[182:185], v[22:25], v[18:21]
	v_mfma_f32_16x16x32_bf16 v[22:25], v[154:157], v[26:29], 0
	v_mfma_f32_16x16x32_bf16 v[26:29], v[170:173], v[26:29], 0
	v_mfma_f32_16x16x32_bf16 v[22:25], v[166:169], v[30:33], v[22:25]
	v_mfma_f32_16x16x32_bf16 v[26:29], v[182:185], v[30:33], v[26:29]
	v_mfma_f32_16x16x32_bf16 v[30:33], v[154:157], v[34:37], 0
	v_mfma_f32_16x16x32_bf16 v[34:37], v[170:173], v[34:37], 0
	v_mfma_f32_16x16x32_bf16 v[30:33], v[166:169], v[38:41], v[30:33]
	v_mfma_f32_16x16x32_bf16 v[34:37], v[182:185], v[38:41], v[34:37]
	v_mfma_f32_16x16x32_bf16 v[38:41], v[154:157], v[42:45], 0
	v_mfma_f32_16x16x32_bf16 v[42:45], v[170:173], v[42:45], 0
	v_mfma_f32_16x16x32_bf16 v[38:41], v[166:169], v[46:49], v[38:41]
	v_mfma_f32_16x16x32_bf16 v[42:45], v[182:185], v[46:49], v[42:45]
	s_mov_b32 m0, s38
	v_lshl_add_u64 v[242:243], s[26:27], 0, v[232:233]
	s_barrier
	ds_read_b128 v[46:49], v222 offset:16384
	ds_read_b128 v[142:145], v222 offset:17408
	ds_read_b128 v[146:149], v222 offset:18432
	ds_read_b128 v[158:161], v222 offset:19456
	ds_read_b128 v[162:165], v222 offset:20480
	ds_read_b128 v[174:177], v222 offset:21504
	ds_read_b128 v[178:181], v222 offset:22528
	ds_read_b128 v[186:189], v222 offset:23552
	global_load_lds_dwordx4 v[242:243], off
	v_lshl_add_u64 v[224:225], s[26:27], 0, v[228:229]
	s_mov_b32 m0, s39
	s_nop 0
	global_load_lds_dwordx4 v[224:225], off
	s_barrier
	s_waitcnt lgkmcnt(0)
	v_mfma_f32_16x16x32_bf16 v[138:141], v[2:5], v[46:49], 0
	v_mfma_f32_16x16x32_bf16 v[134:137], v[10:13], v[46:49], 0
	v_mfma_f32_16x16x32_bf16 v[122:125], v[2:5], v[146:149], 0
	v_mfma_f32_16x16x32_bf16 v[118:121], v[10:13], v[146:149], 0
	v_mfma_f32_16x16x32_bf16 v[106:109], v[2:5], v[162:165], 0
	v_mfma_f32_16x16x32_bf16 v[102:105], v[10:13], v[162:165], 0
	v_mfma_f32_16x16x32_bf16 v[2:5], v[2:5], v[178:181], 0
	v_mfma_f32_16x16x32_bf16 v[138:141], v[6:9], v[142:145], v[138:141]
	v_mfma_f32_16x16x32_bf16 v[134:137], v[14:17], v[142:145], v[134:137]
	v_mfma_f32_16x16x32_bf16 v[122:125], v[6:9], v[158:161], v[122:125]
	v_mfma_f32_16x16x32_bf16 v[118:121], v[14:17], v[158:161], v[118:121]
	v_mfma_f32_16x16x32_bf16 v[106:109], v[6:9], v[174:177], v[106:109]
	v_mfma_f32_16x16x32_bf16 v[102:105], v[14:17], v[174:177], v[102:105]
	v_mfma_f32_16x16x32_bf16 v[2:5], v[6:9], v[186:189], v[2:5]
	v_mfma_f32_16x16x32_bf16 v[6:9], v[10:13], v[178:181], 0
	v_mfma_f32_16x16x32_bf16 v[6:9], v[14:17], v[186:189], v[6:9]
	s_barrier
	s_add_u32 s62, s8, 0x40000
	s_addc_u32 s63, s9, 0
	s_add_i32 s59, s64, s37
	v_lshl_add_u64 v[10:11], s[62:63], 0, v[230:231]
	s_mov_b32 m0, s59
	s_nop 0
	global_load_lds_dwordx4 v[10:11], off
	v_lshl_add_u64 v[10:11], s[62:63], 0, v[226:227]
	s_add_i32 m0, s59, 0x2000
	s_nop 0
	global_load_lds_dwordx4 v[10:11], off
	s_waitcnt vmcnt(6)
	s_barrier
	v_mfma_f32_16x16x32_bf16 v[86:89], v[170:173], v[146:149], 0
	v_mfma_f32_16x16x32_bf16 v[110:113], v[182:185], v[158:161], v[86:89]
	v_mfma_f32_16x16x32_bf16 v[86:89], v[154:157], v[162:165], 0
	v_mfma_f32_16x16x32_bf16 v[98:101], v[166:169], v[174:177], v[86:89]
	v_mfma_f32_16x16x32_bf16 v[86:89], v[170:173], v[162:165], 0
	v_mfma_f32_16x16x32_bf16 v[82:85], v[154:157], v[178:181], 0
	v_mfma_f32_16x16x32_bf16 v[78:81], v[170:173], v[178:181], 0
	v_mfma_f32_16x16x32_bf16 v[10:13], v[154:157], v[46:49], 0
	v_mfma_f32_16x16x32_bf16 v[14:17], v[170:173], v[46:49], 0
	v_mfma_f32_16x16x32_bf16 v[46:49], v[154:157], v[146:149], 0
	v_mfma_f32_16x16x32_bf16 v[94:97], v[182:185], v[174:177], v[86:89]
	v_mfma_f32_16x16x32_bf16 v[82:85], v[166:169], v[186:189], v[82:85]
	v_mfma_f32_16x16x32_bf16 v[78:81], v[182:185], v[186:189], v[78:81]
	v_mfma_f32_16x16x32_bf16 v[10:13], v[166:169], v[142:145], v[10:13]
	v_mfma_f32_16x16x32_bf16 v[14:17], v[182:185], v[142:145], v[14:17]
	v_mfma_f32_16x16x32_bf16 v[46:49], v[166:169], v[158:161], v[46:49]
	s_add_i32 s59, 0, 0x18000
	v_add_u32_e32 v0, s59, v249
	s_barrier
	ds_read_b128 v[86:89], v0
	ds_read_b128 v[90:93], v0 offset:1024
	ds_read_b128 v[114:117], v0 offset:2048
	ds_read_b128 v[126:129], v0 offset:3072
	s_add_u32 s26, s26, 0x40000
	s_addc_u32 s27, s27, 0
	s_mov_b32 m0, s40
	v_lshl_add_u64 v[154:155], s[26:27], 0, v[232:233]
	ds_read_b128 v[130:133], v222 offset:32768
	ds_read_b128 v[142:145], v222 offset:33792
	ds_read_b128 v[146:149], v222 offset:34816
	ds_read_b128 v[158:161], v222 offset:35840
	ds_read_b128 v[206:209], v222 offset:36864
	ds_read_b128 v[210:213], v222 offset:37888
	ds_read_b128 v[214:217], v222 offset:38912
	ds_read_b128 v[218:221], v222 offset:39936
	global_load_lds_dwordx4 v[154:155], off
	v_lshl_add_u64 v[154:155], s[26:27], 0, v[228:229]
	s_mov_b32 m0, s41
	s_nop 0
	global_load_lds_dwordx4 v[154:155], off
	s_waitcnt lgkmcnt(8)
	s_barrier
	s_waitcnt lgkmcnt(0)
	v_mfma_f32_16x16x32_bf16 v[50:53], v[86:89], v[130:133], v[50:53]
	v_mfma_f32_16x16x32_bf16 v[202:205], v[90:93], v[142:145], v[50:53]
	v_mfma_f32_16x16x32_bf16 v[50:53], v[114:117], v[130:133], v[54:57]
	v_mfma_f32_16x16x32_bf16 v[198:201], v[126:129], v[142:145], v[50:53]
	v_mfma_f32_16x16x32_bf16 v[50:53], v[86:89], v[146:149], v[58:61]
	v_mfma_f32_16x16x32_bf16 v[186:189], v[90:93], v[158:161], v[50:53]
	v_mfma_f32_16x16x32_bf16 v[50:53], v[114:117], v[146:149], v[62:65]
	v_mfma_f32_16x16x32_bf16 v[182:185], v[126:129], v[158:161], v[50:53]
	v_mfma_f32_16x16x32_bf16 v[50:53], v[86:89], v[206:209], v[66:69]
	v_mfma_f32_16x16x32_bf16 v[170:173], v[90:93], v[210:213], v[50:53]
	v_mfma_f32_16x16x32_bf16 v[50:53], v[114:117], v[206:209], v[70:73]
	v_mfma_f32_16x16x32_bf16 v[166:169], v[126:129], v[210:213], v[50:53]
	v_mfma_f32_16x16x32_bf16 v[50:53], v[86:89], v[214:217], v[74:77]
	v_mfma_f32_16x16x32_bf16 v[154:157], v[90:93], v[218:221], v[50:53]
	v_mfma_f32_16x16x32_bf16 v[50:53], v[114:117], v[214:217], v[150:153]
	v_mfma_f32_16x16x32_bf16 v[150:153], v[126:129], v[218:221], v[50:53]
	s_barrier
	s_add_i32 s26, 0, 0x1c000
	s_add_i32 s27, s59, s37
	v_add_u32_e32 v0, s26, v249
	v_lshl_add_u64 v[66:67], v[238:239], 0, s[20:21]
	s_mov_b32 m0, s27
	ds_read_b128 v[50:53], v0
	ds_read_b128 v[54:57], v0 offset:1024
	ds_read_b128 v[58:61], v0 offset:2048
	ds_read_b128 v[62:65], v0 offset:3072
	global_load_lds_dwordx4 v[66:67], off
	v_lshl_add_u64 v[66:67], v[240:241], 0, s[20:21]
	s_add_i32 m0, s27, 0x2000
	s_nop 0
	global_load_lds_dwordx4 v[66:67], off
	s_barrier
	s_waitcnt lgkmcnt(0)
	v_mfma_f32_16x16x32_bf16 v[18:21], v[58:61], v[130:133], v[18:21]
	v_mfma_f32_16x16x32_bf16 v[190:193], v[62:65], v[142:145], v[18:21]
	v_mfma_f32_16x16x32_bf16 v[18:21], v[50:53], v[146:149], v[22:25]
	v_mfma_f32_16x16x32_bf16 v[178:181], v[54:57], v[158:161], v[18:21]
	v_mfma_f32_16x16x32_bf16 v[18:21], v[58:61], v[146:149], v[26:29]
	v_mfma_f32_16x16x32_bf16 v[174:177], v[62:65], v[158:161], v[18:21]
	v_mfma_f32_16x16x32_bf16 v[18:21], v[50:53], v[206:209], v[30:33]
	v_mfma_f32_16x16x32_bf16 v[162:165], v[54:57], v[210:213], v[18:21]
	v_mfma_f32_16x16x32_bf16 v[18:21], v[58:61], v[206:209], v[34:37]
	v_mfma_f32_16x16x32_bf16 v[158:161], v[62:65], v[210:213], v[18:21]
	v_mfma_f32_16x16x32_bf16 v[18:21], v[50:53], v[214:217], v[38:41]
	v_mfma_f32_16x16x32_bf16 v[66:69], v[50:53], v[130:133], v[194:197]
	v_mfma_f32_16x16x32_bf16 v[146:149], v[54:57], v[218:221], v[18:21]
	v_mfma_f32_16x16x32_bf16 v[18:21], v[58:61], v[214:217], v[42:45]
	v_mfma_f32_16x16x32_bf16 v[194:197], v[54:57], v[142:145], v[66:69]
	v_mfma_f32_16x16x32_bf16 v[142:145], v[62:65], v[218:221], v[18:21]
	s_mov_b32 m0, s44
	v_lshl_add_u64 v[70:71], v[242:243], 0, s[20:21]
	s_barrier
	s_nop 1
	ds_read_b128 v[18:21], v222 offset:49152
	ds_read_b128 v[22:25], v222 offset:50176
	ds_read_b128 v[26:29], v222 offset:51200
	ds_read_b128 v[30:33], v222 offset:52224
	ds_read_b128 v[34:37], v222 offset:53248
	ds_read_b128 v[38:41], v222 offset:54272
	ds_read_b128 v[42:45], v222 offset:55296
	ds_read_b128 v[66:69], v222 offset:56320
	global_load_lds_dwordx4 v[70:71], off
	v_lshl_add_u64 v[70:71], v[224:225], 0, s[20:21]
	s_mov_b32 m0, s45
	s_nop 0
	global_load_lds_dwordx4 v[70:71], off
	s_barrier
	s_waitcnt lgkmcnt(0)
	v_mfma_f32_16x16x32_bf16 v[70:73], v[86:89], v[18:21], v[138:141]
	v_mfma_f32_16x16x32_bf16 v[138:141], v[90:93], v[22:25], v[70:73]
	v_mfma_f32_16x16x32_bf16 v[70:73], v[114:117], v[18:21], v[134:137]
	v_mfma_f32_16x16x32_bf16 v[134:137], v[126:129], v[22:25], v[70:73]
	v_mfma_f32_16x16x32_bf16 v[70:73], v[86:89], v[26:29], v[122:125]
	v_mfma_f32_16x16x32_bf16 v[122:125], v[90:93], v[30:33], v[70:73]
	v_mfma_f32_16x16x32_bf16 v[70:73], v[114:117], v[26:29], v[118:121]
	v_mfma_f32_16x16x32_bf16 v[118:121], v[126:129], v[30:33], v[70:73]
	v_mfma_f32_16x16x32_bf16 v[70:73], v[86:89], v[34:37], v[106:109]
	v_mfma_f32_16x16x32_bf16 v[2:5], v[86:89], v[42:45], v[2:5]
	v_mfma_f32_16x16x32_bf16 v[106:109], v[90:93], v[38:41], v[70:73]
	v_mfma_f32_16x16x32_bf16 v[70:73], v[114:117], v[34:37], v[102:105]
	v_mfma_f32_16x16x32_bf16 v[90:93], v[90:93], v[66:69], v[2:5]
	v_mfma_f32_16x16x32_bf16 v[2:5], v[114:117], v[42:45], v[6:9]
	v_mfma_f32_16x16x32_bf16 v[102:105], v[126:129], v[38:41], v[70:73]
	v_mfma_f32_16x16x32_bf16 v[86:89], v[126:129], v[66:69], v[2:5]
	s_barrier
	s_add_u32 s8, s8, 0x40080
	s_addc_u32 s9, s9, 0
	s_add_i32 s26, s26, s37
	s_nop 0
	v_lshl_add_u64 v[2:3], s[8:9], 0, v[230:231]
	s_mov_b32 m0, s26
	s_nop 0
	global_load_lds_dwordx4 v[2:3], off
	v_lshl_add_u64 v[2:3], s[8:9], 0, v[226:227]
	s_add_i32 m0, s26, 0x2000
	s_nop 0
	global_load_lds_dwordx4 v[2:3], off
	s_waitcnt vmcnt(6)
	s_barrier
	v_mfma_f32_16x16x32_bf16 v[2:5], v[50:53], v[18:21], v[10:13]
	v_mfma_f32_16x16x32_bf16 v[130:133], v[54:57], v[22:25], v[2:5]
	v_mfma_f32_16x16x32_bf16 v[2:5], v[58:61], v[18:21], v[14:17]
	v_mfma_f32_16x16x32_bf16 v[126:129], v[62:65], v[22:25], v[2:5]
	v_mfma_f32_16x16x32_bf16 v[2:5], v[50:53], v[26:29], v[46:49]
	v_mfma_f32_16x16x32_bf16 v[114:117], v[54:57], v[30:33], v[2:5]
	v_mfma_f32_16x16x32_bf16 v[2:5], v[58:61], v[26:29], v[110:113]
	v_mfma_f32_16x16x32_bf16 v[110:113], v[62:65], v[30:33], v[2:5]
	v_mfma_f32_16x16x32_bf16 v[2:5], v[50:53], v[34:37], v[98:101]
	v_mfma_f32_16x16x32_bf16 v[98:101], v[54:57], v[38:41], v[2:5]
	v_mfma_f32_16x16x32_bf16 v[2:5], v[58:61], v[34:37], v[94:97]
	v_mfma_f32_16x16x32_bf16 v[94:97], v[62:65], v[38:41], v[2:5]
	v_mfma_f32_16x16x32_bf16 v[2:5], v[50:53], v[42:45], v[82:85]
	v_mfma_f32_16x16x32_bf16 v[82:85], v[54:57], v[66:69], v[2:5]
	v_mfma_f32_16x16x32_bf16 v[2:5], v[58:61], v[42:45], v[78:81]
	v_mfma_f32_16x16x32_bf16 v[78:81], v[62:65], v[66:69], v[2:5]
	s_add_i32 s58, s58, 2
	s_add_u32 s6, s6, 0x100
	s_addc_u32 s7, s7, 0
	s_add_u32 s56, s56, 0x100
	s_addc_u32 s57, s57, 0
	s_cmp_gt_u32 s58, 13
	s_barrier
	s_cbranch_scc0 .LBB0_1152
	s_branch .Lpeel_exit_g3
.LBB0_1152:
	s_add_u32 s8, s6, 0xfffc0080
	s_addc_u32 s9, s7, -1
	s_add_i32 s59, 0, 0x10000
	v_add_u32_e32 v0, s59, v249
	ds_read_b128 v[2:5], v0
	ds_read_b128 v[6:9], v0 offset:1024
	ds_read_b128 v[10:13], v0 offset:2048
	ds_read_b128 v[14:17], v0 offset:3072
	s_cmp_eq_u32 s58, 12
	s_cselect_b32 s27, s13, s9
	s_cselect_b32 s26, s54, s8
	s_cselect_b32 s9, s11, s57
	s_cselect_b32 s8, s55, s56
	v_lshl_add_u64 v[50:51], s[6:7], 0, v[234:235]
	s_add_i32 m0, s38, 0xc000
	ds_read_b128 v[18:21], v222
	ds_read_b128 v[22:25], v222 offset:1024
	ds_read_b128 v[26:29], v222 offset:2048
	ds_read_b128 v[30:33], v222 offset:3072
	ds_read_b128 v[34:37], v222 offset:4096
	ds_read_b128 v[38:41], v222 offset:5120
	ds_read_b128 v[42:45], v222 offset:6144
	ds_read_b128 v[46:49], v222 offset:7168
	global_load_lds_dwordx4 v[50:51], off
	v_lshl_add_u64 v[50:51], s[6:7], 0, v[236:237]
	s_add_i32 m0, s38, 0xe000
	s_nop 0
	global_load_lds_dwordx4 v[50:51], off
	s_waitcnt lgkmcnt(8)
	s_barrier
	s_waitcnt lgkmcnt(0)
	v_mfma_f32_16x16x32_bf16 v[150:153], v[10:13], v[42:45], v[150:153]
	v_mfma_f32_16x16x32_bf16 v[50:53], v[2:5], v[18:21], v[202:205]
	v_mfma_f32_16x16x32_bf16 v[54:57], v[10:13], v[18:21], v[198:201]
	v_mfma_f32_16x16x32_bf16 v[58:61], v[2:5], v[26:29], v[186:189]
	v_mfma_f32_16x16x32_bf16 v[62:65], v[10:13], v[26:29], v[182:185]
	v_mfma_f32_16x16x32_bf16 v[66:69], v[2:5], v[34:37], v[170:173]
	v_mfma_f32_16x16x32_bf16 v[70:73], v[10:13], v[34:37], v[166:169]
	v_mfma_f32_16x16x32_bf16 v[74:77], v[2:5], v[42:45], v[154:157]
	v_mfma_f32_16x16x32_bf16 v[150:153], v[14:17], v[46:49], v[150:153]
	v_mfma_f32_16x16x32_bf16 v[50:53], v[6:9], v[22:25], v[50:53]
	v_mfma_f32_16x16x32_bf16 v[54:57], v[14:17], v[22:25], v[54:57]
	v_mfma_f32_16x16x32_bf16 v[58:61], v[6:9], v[30:33], v[58:61]
	v_mfma_f32_16x16x32_bf16 v[62:65], v[14:17], v[30:33], v[62:65]
	v_mfma_f32_16x16x32_bf16 v[66:69], v[6:9], v[38:41], v[66:69]
	v_mfma_f32_16x16x32_bf16 v[70:73], v[14:17], v[38:41], v[70:73]
	v_mfma_f32_16x16x32_bf16 v[74:77], v[6:9], v[46:49], v[74:77]
	s_barrier
	s_add_i32 s64, 0, 0x14000
	s_add_i32 s59, s59, s37
	v_add_u32_e32 v0, s64, v249
	v_lshl_add_u64 v[238:239], s[8:9], 0, v[230:231]
	s_mov_b32 m0, s59
	ds_read_b128 v[154:157], v0
	ds_read_b128 v[166:169], v0 offset:1024
	ds_read_b128 v[170:173], v0 offset:2048
	ds_read_b128 v[182:185], v0 offset:3072
	global_load_lds_dwordx4 v[238:239], off
	v_lshl_add_u64 v[240:241], s[8:9], 0, v[226:227]
	s_add_i32 m0, s59, 0x2000
	s_nop 0
	global_load_lds_dwordx4 v[240:241], off
	s_barrier
	s_waitcnt lgkmcnt(0)
	v_mfma_f32_16x16x32_bf16 v[186:189], v[154:157], v[18:21], v[194:197]
	v_mfma_f32_16x16x32_bf16 v[18:21], v[170:173], v[18:21], v[190:193]
	v_mfma_f32_16x16x32_bf16 v[194:197], v[166:169], v[22:25], v[186:189]
	v_mfma_f32_16x16x32_bf16 v[18:21], v[182:185], v[22:25], v[18:21]
	v_mfma_f32_16x16x32_bf16 v[22:25], v[154:157], v[26:29], v[178:181]
	v_mfma_f32_16x16x32_bf16 v[26:29], v[170:173], v[26:29], v[174:177]
	v_mfma_f32_16x16x32_bf16 v[22:25], v[166:169], v[30:33], v[22:25]
	v_mfma_f32_16x16x32_bf16 v[26:29], v[182:185], v[30:33], v[26:29]
	v_mfma_f32_16x16x32_bf16 v[30:33], v[154:157], v[34:37], v[162:165]
	v_mfma_f32_16x16x32_bf16 v[34:37], v[170:173], v[34:37], v[158:161]
	v_mfma_f32_16x16x32_bf16 v[30:33], v[166:169], v[38:41], v[30:33]
	v_mfma_f32_16x16x32_bf16 v[34:37], v[182:185], v[38:41], v[34:37]
	v_mfma_f32_16x16x32_bf16 v[38:41], v[154:157], v[42:45], v[146:149]
	v_mfma_f32_16x16x32_bf16 v[42:45], v[170:173], v[42:45], v[142:145]
	v_mfma_f32_16x16x32_bf16 v[38:41], v[166:169], v[46:49], v[38:41]
	v_mfma_f32_16x16x32_bf16 v[42:45], v[182:185], v[46:49], v[42:45]
	s_mov_b32 m0, s38
	v_lshl_add_u64 v[242:243], s[26:27], 0, v[232:233]
	s_barrier
	ds_read_b128 v[46:49], v222 offset:16384
	ds_read_b128 v[142:145], v222 offset:17408
	ds_read_b128 v[146:149], v222 offset:18432
	ds_read_b128 v[158:161], v222 offset:19456
	ds_read_b128 v[162:165], v222 offset:20480
	ds_read_b128 v[174:177], v222 offset:21504
	ds_read_b128 v[178:181], v222 offset:22528
	ds_read_b128 v[186:189], v222 offset:23552
	global_load_lds_dwordx4 v[242:243], off
	v_lshl_add_u64 v[224:225], s[26:27], 0, v[228:229]
	s_mov_b32 m0, s39
	s_nop 0
	global_load_lds_dwordx4 v[224:225], off
	s_barrier
	s_waitcnt lgkmcnt(0)
	v_mfma_f32_16x16x32_bf16 v[138:141], v[2:5], v[46:49], v[138:141]
	v_mfma_f32_16x16x32_bf16 v[134:137], v[10:13], v[46:49], v[134:137]
	v_mfma_f32_16x16x32_bf16 v[122:125], v[2:5], v[146:149], v[122:125]
	v_mfma_f32_16x16x32_bf16 v[118:121], v[10:13], v[146:149], v[118:121]
	v_mfma_f32_16x16x32_bf16 v[106:109], v[2:5], v[162:165], v[106:109]
	v_mfma_f32_16x16x32_bf16 v[102:105], v[10:13], v[162:165], v[102:105]
	v_mfma_f32_16x16x32_bf16 v[2:5], v[2:5], v[178:181], v[90:93]
	v_mfma_f32_16x16x32_bf16 v[138:141], v[6:9], v[142:145], v[138:141]
	v_mfma_f32_16x16x32_bf16 v[134:137], v[14:17], v[142:145], v[134:137]
	v_mfma_f32_16x16x32_bf16 v[122:125], v[6:9], v[158:161], v[122:125]
	v_mfma_f32_16x16x32_bf16 v[118:121], v[14:17], v[158:161], v[118:121]
	v_mfma_f32_16x16x32_bf16 v[106:109], v[6:9], v[174:177], v[106:109]
	v_mfma_f32_16x16x32_bf16 v[102:105], v[14:17], v[174:177], v[102:105]
	v_mfma_f32_16x16x32_bf16 v[2:5], v[6:9], v[186:189], v[2:5]
	v_mfma_f32_16x16x32_bf16 v[6:9], v[10:13], v[178:181], v[86:89]
	v_mfma_f32_16x16x32_bf16 v[6:9], v[14:17], v[186:189], v[6:9]
	s_barrier
	s_add_u32 s62, s8, 0x40000
	s_addc_u32 s63, s9, 0
	s_add_i32 s59, s64, s37
	v_lshl_add_u64 v[10:11], s[62:63], 0, v[230:231]
	s_mov_b32 m0, s59
	s_nop 0
	global_load_lds_dwordx4 v[10:11], off
	v_lshl_add_u64 v[10:11], s[62:63], 0, v[226:227]
	s_add_i32 m0, s59, 0x2000
	s_nop 0
	global_load_lds_dwordx4 v[10:11], off
	s_waitcnt vmcnt(6)
	s_barrier
	v_mfma_f32_16x16x32_bf16 v[86:89], v[170:173], v[146:149], v[110:113]
	v_mfma_f32_16x16x32_bf16 v[110:113], v[182:185], v[158:161], v[86:89]
	v_mfma_f32_16x16x32_bf16 v[86:89], v[154:157], v[162:165], v[98:101]
	v_mfma_f32_16x16x32_bf16 v[98:101], v[166:169], v[174:177], v[86:89]
	v_mfma_f32_16x16x32_bf16 v[86:89], v[170:173], v[162:165], v[94:97]
	v_mfma_f32_16x16x32_bf16 v[82:85], v[154:157], v[178:181], v[82:85]
	v_mfma_f32_16x16x32_bf16 v[78:81], v[170:173], v[178:181], v[78:81]
	v_mfma_f32_16x16x32_bf16 v[10:13], v[154:157], v[46:49], v[130:133]
	v_mfma_f32_16x16x32_bf16 v[14:17], v[170:173], v[46:49], v[126:129]
	v_mfma_f32_16x16x32_bf16 v[46:49], v[154:157], v[146:149], v[114:117]
	v_mfma_f32_16x16x32_bf16 v[94:97], v[182:185], v[174:177], v[86:89]
	v_mfma_f32_16x16x32_bf16 v[82:85], v[166:169], v[186:189], v[82:85]
	v_mfma_f32_16x16x32_bf16 v[78:81], v[182:185], v[186:189], v[78:81]
	v_mfma_f32_16x16x32_bf16 v[10:13], v[166:169], v[142:145], v[10:13]
	v_mfma_f32_16x16x32_bf16 v[14:17], v[182:185], v[142:145], v[14:17]
	v_mfma_f32_16x16x32_bf16 v[46:49], v[166:169], v[158:161], v[46:49]
	s_add_i32 s59, 0, 0x18000
	v_add_u32_e32 v0, s59, v249
	s_barrier
	ds_read_b128 v[86:89], v0
	ds_read_b128 v[90:93], v0 offset:1024
	ds_read_b128 v[114:117], v0 offset:2048
	ds_read_b128 v[126:129], v0 offset:3072
	s_add_u32 s26, s26, 0x40000
	s_addc_u32 s27, s27, 0
	s_mov_b32 m0, s40
	v_lshl_add_u64 v[154:155], s[26:27], 0, v[232:233]
	ds_read_b128 v[130:133], v222 offset:32768
	ds_read_b128 v[142:145], v222 offset:33792
	ds_read_b128 v[146:149], v222 offset:34816
	ds_read_b128 v[158:161], v222 offset:35840
	ds_read_b128 v[206:209], v222 offset:36864
	ds_read_b128 v[210:213], v222 offset:37888
	ds_read_b128 v[214:217], v222 offset:38912
	ds_read_b128 v[218:221], v222 offset:39936
	global_load_lds_dwordx4 v[154:155], off
	v_lshl_add_u64 v[154:155], s[26:27], 0, v[228:229]
	s_mov_b32 m0, s41
	s_nop 0
	global_load_lds_dwordx4 v[154:155], off
	s_waitcnt lgkmcnt(8)
	s_barrier
	s_waitcnt lgkmcnt(0)
	v_mfma_f32_16x16x32_bf16 v[50:53], v[86:89], v[130:133], v[50:53]
	v_mfma_f32_16x16x32_bf16 v[202:205], v[90:93], v[142:145], v[50:53]
	v_mfma_f32_16x16x32_bf16 v[50:53], v[114:117], v[130:133], v[54:57]
	v_mfma_f32_16x16x32_bf16 v[198:201], v[126:129], v[142:145], v[50:53]
	v_mfma_f32_16x16x32_bf16 v[50:53], v[86:89], v[146:149], v[58:61]
	v_mfma_f32_16x16x32_bf16 v[186:189], v[90:93], v[158:161], v[50:53]
	v_mfma_f32_16x16x32_bf16 v[50:53], v[114:117], v[146:149], v[62:65]
	v_mfma_f32_16x16x32_bf16 v[182:185], v[126:129], v[158:161], v[50:53]
	v_mfma_f32_16x16x32_bf16 v[50:53], v[86:89], v[206:209], v[66:69]
	v_mfma_f32_16x16x32_bf16 v[170:173], v[90:93], v[210:213], v[50:53]
	v_mfma_f32_16x16x32_bf16 v[50:53], v[114:117], v[206:209], v[70:73]
	v_mfma_f32_16x16x32_bf16 v[166:169], v[126:129], v[210:213], v[50:53]
	v_mfma_f32_16x16x32_bf16 v[50:53], v[86:89], v[214:217], v[74:77]
	v_mfma_f32_16x16x32_bf16 v[154:157], v[90:93], v[218:221], v[50:53]
	v_mfma_f32_16x16x32_bf16 v[50:53], v[114:117], v[214:217], v[150:153]
	v_mfma_f32_16x16x32_bf16 v[150:153], v[126:129], v[218:221], v[50:53]
	s_barrier
	s_add_i32 s26, 0, 0x1c000
	s_add_i32 s27, s59, s37
	v_add_u32_e32 v0, s26, v249
	v_lshl_add_u64 v[66:67], v[238:239], 0, s[20:21]
	s_mov_b32 m0, s27
	ds_read_b128 v[50:53], v0
	ds_read_b128 v[54:57], v0 offset:1024
	ds_read_b128 v[58:61], v0 offset:2048
	ds_read_b128 v[62:65], v0 offset:3072
	global_load_lds_dwordx4 v[66:67], off
	v_lshl_add_u64 v[66:67], v[240:241], 0, s[20:21]
	s_add_i32 m0, s27, 0x2000
	s_nop 0
	global_load_lds_dwordx4 v[66:67], off
	s_barrier
	s_waitcnt lgkmcnt(0)
	v_mfma_f32_16x16x32_bf16 v[18:21], v[58:61], v[130:133], v[18:21]
	v_mfma_f32_16x16x32_bf16 v[190:193], v[62:65], v[142:145], v[18:21]
	v_mfma_f32_16x16x32_bf16 v[18:21], v[50:53], v[146:149], v[22:25]
	v_mfma_f32_16x16x32_bf16 v[178:181], v[54:57], v[158:161], v[18:21]
	v_mfma_f32_16x16x32_bf16 v[18:21], v[58:61], v[146:149], v[26:29]
	v_mfma_f32_16x16x32_bf16 v[174:177], v[62:65], v[158:161], v[18:21]
	v_mfma_f32_16x16x32_bf16 v[18:21], v[50:53], v[206:209], v[30:33]
	v_mfma_f32_16x16x32_bf16 v[162:165], v[54:57], v[210:213], v[18:21]
	v_mfma_f32_16x16x32_bf16 v[18:21], v[58:61], v[206:209], v[34:37]
	v_mfma_f32_16x16x32_bf16 v[158:161], v[62:65], v[210:213], v[18:21]
	v_mfma_f32_16x16x32_bf16 v[18:21], v[50:53], v[214:217], v[38:41]
	v_mfma_f32_16x16x32_bf16 v[66:69], v[50:53], v[130:133], v[194:197]
	v_mfma_f32_16x16x32_bf16 v[146:149], v[54:57], v[218:221], v[18:21]
	v_mfma_f32_16x16x32_bf16 v[18:21], v[58:61], v[214:217], v[42:45]
	v_mfma_f32_16x16x32_bf16 v[194:197], v[54:57], v[142:145], v[66:69]
	v_mfma_f32_16x16x32_bf16 v[142:145], v[62:65], v[218:221], v[18:21]
	s_mov_b32 m0, s44
	v_lshl_add_u64 v[70:71], v[242:243], 0, s[20:21]
	s_barrier
	s_nop 1
	ds_read_b128 v[18:21], v222 offset:49152
	ds_read_b128 v[22:25], v222 offset:50176
	ds_read_b128 v[26:29], v222 offset:51200
	ds_read_b128 v[30:33], v222 offset:52224
	ds_read_b128 v[34:37], v222 offset:53248
	ds_read_b128 v[38:41], v222 offset:54272
	ds_read_b128 v[42:45], v222 offset:55296
	ds_read_b128 v[66:69], v222 offset:56320
	global_load_lds_dwordx4 v[70:71], off
	v_lshl_add_u64 v[70:71], v[224:225], 0, s[20:21]
	s_mov_b32 m0, s45
	s_nop 0
	global_load_lds_dwordx4 v[70:71], off
	s_barrier
	s_waitcnt lgkmcnt(0)
	v_mfma_f32_16x16x32_bf16 v[70:73], v[86:89], v[18:21], v[138:141]
	v_mfma_f32_16x16x32_bf16 v[138:141], v[90:93], v[22:25], v[70:73]
	v_mfma_f32_16x16x32_bf16 v[70:73], v[114:117], v[18:21], v[134:137]
	v_mfma_f32_16x16x32_bf16 v[134:137], v[126:129], v[22:25], v[70:73]
	v_mfma_f32_16x16x32_bf16 v[70:73], v[86:89], v[26:29], v[122:125]
	v_mfma_f32_16x16x32_bf16 v[122:125], v[90:93], v[30:33], v[70:73]
	v_mfma_f32_16x16x32_bf16 v[70:73], v[114:117], v[26:29], v[118:121]
	v_mfma_f32_16x16x32_bf16 v[118:121], v[126:129], v[30:33], v[70:73]
	v_mfma_f32_16x16x32_bf16 v[70:73], v[86:89], v[34:37], v[106:109]
	v_mfma_f32_16x16x32_bf16 v[2:5], v[86:89], v[42:45], v[2:5]
	v_mfma_f32_16x16x32_bf16 v[106:109], v[90:93], v[38:41], v[70:73]
	v_mfma_f32_16x16x32_bf16 v[70:73], v[114:117], v[34:37], v[102:105]
	v_mfma_f32_16x16x32_bf16 v[90:93], v[90:93], v[66:69], v[2:5]
	v_mfma_f32_16x16x32_bf16 v[2:5], v[114:117], v[42:45], v[6:9]
	v_mfma_f32_16x16x32_bf16 v[102:105], v[126:129], v[38:41], v[70:73]
	v_mfma_f32_16x16x32_bf16 v[86:89], v[126:129], v[66:69], v[2:5]
	s_barrier
	s_add_u32 s8, s8, 0x40080
	s_addc_u32 s9, s9, 0
	s_add_i32 s26, s26, s37
	s_nop 0
	v_lshl_add_u64 v[2:3], s[8:9], 0, v[230:231]
	s_mov_b32 m0, s26
	s_nop 0
	global_load_lds_dwordx4 v[2:3], off
	v_lshl_add_u64 v[2:3], s[8:9], 0, v[226:227]
	s_add_i32 m0, s26, 0x2000
	s_nop 0
	global_load_lds_dwordx4 v[2:3], off
	s_waitcnt vmcnt(6)
	s_barrier
	v_mfma_f32_16x16x32_bf16 v[2:5], v[50:53], v[18:21], v[10:13]
	v_mfma_f32_16x16x32_bf16 v[130:133], v[54:57], v[22:25], v[2:5]
	v_mfma_f32_16x16x32_bf16 v[2:5], v[58:61], v[18:21], v[14:17]
	v_mfma_f32_16x16x32_bf16 v[126:129], v[62:65], v[22:25], v[2:5]
	v_mfma_f32_16x16x32_bf16 v[2:5], v[50:53], v[26:29], v[46:49]
	v_mfma_f32_16x16x32_bf16 v[114:117], v[54:57], v[30:33], v[2:5]
	v_mfma_f32_16x16x32_bf16 v[2:5], v[58:61], v[26:29], v[110:113]
	v_mfma_f32_16x16x32_bf16 v[110:113], v[62:65], v[30:33], v[2:5]
	v_mfma_f32_16x16x32_bf16 v[2:5], v[50:53], v[34:37], v[98:101]
	v_mfma_f32_16x16x32_bf16 v[98:101], v[54:57], v[38:41], v[2:5]
	v_mfma_f32_16x16x32_bf16 v[2:5], v[58:61], v[34:37], v[94:97]
	v_mfma_f32_16x16x32_bf16 v[94:97], v[62:65], v[38:41], v[2:5]
	v_mfma_f32_16x16x32_bf16 v[2:5], v[50:53], v[42:45], v[82:85]
	v_mfma_f32_16x16x32_bf16 v[82:85], v[54:57], v[66:69], v[2:5]
	v_mfma_f32_16x16x32_bf16 v[2:5], v[58:61], v[42:45], v[78:81]
	v_mfma_f32_16x16x32_bf16 v[78:81], v[62:65], v[66:69], v[2:5]
	s_add_i32 s58, s58, 2
	s_add_u32 s6, s6, 0x100
	s_addc_u32 s7, s7, 0
	s_add_u32 s56, s56, 0x100
	s_addc_u32 s57, s57, 0
	s_cmp_gt_u32 s58, 13
	s_barrier
	s_cbranch_scc0 .LBB0_1152
